# g12 + P6/P9 out-projection epilogue store loops rewritten: all residual loads issued up front into dead accumulator registers, counted waits
# baseline (speedup 1.0000x reference)
; DI f32x4 mfma16(bf16x8 a, bf16x8 b, f32x4 c) { return __builtin_amdgcn_mfma_f32_16x16x32_bf16(a, b, c, 0, 0, 0); }
; template <int NI, class XL, class EP>
; DI void gemm_tile(const u16* __restrict__ W, int ldw, int f0, int t0, int K, XL xl, EP ep, unsigned char* smem) {
;     ...
;   for (int it = 0; it < nk; ++it) {
;     const u16* Ws = S0 + (it & 1) * BUF; const u16* Xs = Ws + 128 * LST;
;     __builtin_amdgcn_s_setprio(1);
;     bf16x8 a[4];
; #pragma unroll
;     for (int mi = 0; mi < 4; ++mi) a[mi] = *(const bf16x8*)(Ws + (wf * 64 + mi * 16 + lr) * LST + lq * 8);
; #pragma unroll
;     for (int ni = 0; ni < NI; ++ni) {
;       const bf16x8 b = *(const bf16x8*)(Xs + (wt * (NI * 16) + ni * 16 + lr) * LST + lq * 8);
; #pragma unroll
;       for (int mi = 0; mi < 4; ++mi) acc[mi][ni] = mfma16(a[mi], b, acc[mi][ni]);
;     }
;     __builtin_amdgcn_sched_group_barrier(0x100, 6, 0);
; #pragma unroll
;     for (int ni = 0; ni < NI; ++ni) { __builtin_amdgcn_sched_group_barrier(0x008, 4, 0); if (ni + 2 < NI) __builtin_amdgcn_sched_group_barrier(0x100, 1, 0); }
;     __builtin_amdgcn_s_setprio(0);
;     if (it + 1 < nk) lstore((it + 1) & 1);
;     if (it + 2 < nk) gload(it + 2);
;     __syncthreads();
;   }
.LBB0_812:
	s_setprio 1
	ds_read_b128 v[168:171], v228 offset:0
	ds_read_b128 v[172:175], v228 offset:1536
	ds_read_b128 v[180:183], v228 offset:3072
	ds_read_b128 v[184:187], v228 offset:4608
	ds_read_b128 v[176:179], v152 offset:12288
	ds_read_b128 v[188:191], v152 offset:13824
	s_waitcnt lgkmcnt(1)
	v_mfma_f32_16x16x32_bf16 v[148:151], v[168:171], v[176:179], v[148:151]
	v_mfma_f32_16x16x32_bf16 v[136:139], v[172:175], v[176:179], v[136:139]
	v_mfma_f32_16x16x32_bf16 v[112:115], v[180:183], v[176:179], v[112:115]
	v_mfma_f32_16x16x32_bf16 v[80:83], v[184:187], v[176:179], v[80:83]
	ds_read_b128 v[176:179], v152 offset:15360
	s_waitcnt vmcnt(6)
	ds_write_b128 v229, v[20:23] offset:36864
	s_waitcnt lgkmcnt(2)
	v_mfma_f32_16x16x32_bf16 v[144:147], v[168:171], v[188:191], v[144:147]
	v_mfma_f32_16x16x32_bf16 v[128:131], v[172:175], v[188:191], v[128:131]
	v_mfma_f32_16x16x32_bf16 v[100:103], v[180:183], v[188:191], v[100:103]
	v_mfma_f32_16x16x32_bf16 v[68:71], v[184:187], v[188:191], v[68:71]
	ds_read_b128 v[188:191], v152 offset:16896
	ds_write_b128 v229, v[16:19] offset:36960
	global_load_dwordx4 v[20:23], v154, s[98:99]
	global_load_dwordx4 v[16:19], v154, s[98:99] offset:64
	s_waitcnt lgkmcnt(3)
	v_mfma_f32_16x16x32_bf16 v[140:143], v[168:171], v[176:179], v[140:143]
	v_mfma_f32_16x16x32_bf16 v[120:123], v[172:175], v[176:179], v[120:123]
	v_mfma_f32_16x16x32_bf16 v[88:91], v[180:183], v[176:179], v[88:91]
	v_mfma_f32_16x16x32_bf16 v[44:47], v[184:187], v[176:179], v[44:47]
	ds_read_b128 v[176:179], v152 offset:18432
	ds_write_b128 v230, v[36:39] offset:49152
	global_load_dwordx4 v[36:39], v156, s[100:101] offset:2048
	s_waitcnt lgkmcnt(3)
	v_mfma_f32_16x16x32_bf16 v[132:135], v[168:171], v[188:191], v[132:135]
	v_mfma_f32_16x16x32_bf16 v[108:111], v[172:175], v[188:191], v[108:111]
	v_mfma_f32_16x16x32_bf16 v[76:79], v[180:183], v[188:191], v[76:79]
	v_mfma_f32_16x16x32_bf16 v[40:43], v[184:187], v[188:191], v[40:43]
	ds_read_b128 v[188:191], v152 offset:19968
	ds_write_b128 v230, v[32:35] offset:49248
	global_load_dwordx4 v[32:35], v156, s[100:101] offset:2112
	s_waitcnt lgkmcnt(3)
	v_mfma_f32_16x16x32_bf16 v[124:127], v[168:171], v[176:179], v[124:127]
	v_mfma_f32_16x16x32_bf16 v[96:99], v[172:175], v[176:179], v[96:99]
	v_mfma_f32_16x16x32_bf16 v[64:67], v[180:183], v[176:179], v[64:67]
	v_mfma_f32_16x16x32_bf16 v[12:15], v[184:187], v[176:179], v[12:15]
	ds_read_b128 v[176:179], v152 offset:21504
	ds_write_b128 v230, v[28:31] offset:49344
	global_load_dwordx4 v[28:31], v156, s[100:101] offset:2176
	s_waitcnt lgkmcnt(3)
	v_mfma_f32_16x16x32_bf16 v[116:119], v[168:171], v[188:191], v[116:119]
	v_mfma_f32_16x16x32_bf16 v[84:87], v[172:175], v[188:191], v[84:87]
	v_mfma_f32_16x16x32_bf16 v[56:59], v[180:183], v[188:191], v[56:59]
	v_mfma_f32_16x16x32_bf16 v[8:11], v[184:187], v[188:191], v[8:11]
	ds_read_b128 v[188:191], v152 offset:23040
	ds_write_b128 v230, v[24:27] offset:49440
	global_load_dwordx4 v[24:27], v156, s[100:101] offset:2240
	s_waitcnt lgkmcnt(3)
	v_mfma_f32_16x16x32_bf16 v[104:107], v[168:171], v[176:179], v[104:107]
	v_mfma_f32_16x16x32_bf16 v[72:75], v[172:175], v[176:179], v[72:75]
	v_mfma_f32_16x16x32_bf16 v[52:55], v[180:183], v[176:179], v[52:55]
	v_mfma_f32_16x16x32_bf16 v[4:7], v[184:187], v[176:179], v[4:7]
	s_add_u32 s98, s98, s18
	s_addc_u32 s99, s99, s19
	s_add_u32 s100, s100, s10
	s_addc_u32 s101, s101, s11
	s_waitcnt lgkmcnt(1)
	v_mfma_f32_16x16x32_bf16 v[92:95], v[168:171], v[188:191], v[92:95]
	v_mfma_f32_16x16x32_bf16 v[60:63], v[172:175], v[188:191], v[60:63]
	v_mfma_f32_16x16x32_bf16 v[48:51], v[180:183], v[188:191], v[48:51]
	v_mfma_f32_16x16x32_bf16 v[0:3], v[184:187], v[188:191], v[0:3]
	s_setprio 0
	s_waitcnt lgkmcnt(0)
	s_barrier
	s_setprio 1
	ds_read_b128 v[168:171], v228 offset:36864
	ds_read_b128 v[172:175], v228 offset:38400
	ds_read_b128 v[180:183], v228 offset:39936
	ds_read_b128 v[184:187], v228 offset:41472
	ds_read_b128 v[176:179], v152 offset:49152
	ds_read_b128 v[188:191], v152 offset:50688
	s_waitcnt lgkmcnt(1)
	v_mfma_f32_16x16x32_bf16 v[148:151], v[168:171], v[176:179], v[148:151]
	v_mfma_f32_16x16x32_bf16 v[136:139], v[172:175], v[176:179], v[136:139]
	v_mfma_f32_16x16x32_bf16 v[112:115], v[180:183], v[176:179], v[112:115]
	v_mfma_f32_16x16x32_bf16 v[80:83], v[184:187], v[176:179], v[80:83]
	ds_read_b128 v[176:179], v152 offset:52224
	s_waitcnt vmcnt(6)
	ds_write_b128 v229, v[200:203] offset:0
	s_waitcnt lgkmcnt(2)
	v_mfma_f32_16x16x32_bf16 v[144:147], v[168:171], v[188:191], v[144:147]
	v_mfma_f32_16x16x32_bf16 v[128:131], v[172:175], v[188:191], v[128:131]
	v_mfma_f32_16x16x32_bf16 v[100:103], v[180:183], v[188:191], v[100:103]
	v_mfma_f32_16x16x32_bf16 v[68:71], v[184:187], v[188:191], v[68:71]
	ds_read_b128 v[188:191], v152 offset:53760
	ds_write_b128 v229, v[204:207] offset:96
	global_load_dwordx4 v[200:203], v154, s[98:99]
	global_load_dwordx4 v[204:207], v154, s[98:99] offset:64
	s_waitcnt lgkmcnt(3)
	v_mfma_f32_16x16x32_bf16 v[140:143], v[168:171], v[176:179], v[140:143]
	v_mfma_f32_16x16x32_bf16 v[120:123], v[172:175], v[176:179], v[120:123]
	v_mfma_f32_16x16x32_bf16 v[88:91], v[180:183], v[176:179], v[88:91]
	v_mfma_f32_16x16x32_bf16 v[44:47], v[184:187], v[176:179], v[44:47]
	ds_read_b128 v[176:179], v152 offset:55296
	ds_write_b128 v230, v[208:211] offset:12288
	global_load_dwordx4 v[208:211], v156, s[100:101] offset:2048
	s_waitcnt lgkmcnt(3)
; DI f32x4 mfma16(bf16x8 a, bf16x8 b, f32x4 c) { return __builtin_amdgcn_mfma_f32_16x16x32_bf16(a, b, c, 0, 0, 0); }
; template <int NI, class XL, class EP>
; DI void gemm_tile(const u16* __restrict__ W, int ldw, int f0, int t0, int K, XL xl, EP ep, unsigned char* smem) {
;     ...
;   for (int it = 0; it < nk; ++it) {
;     const u16* Ws = S0 + (it & 1) * BUF; const u16* Xs = Ws + 128 * LST;
;     __builtin_amdgcn_s_setprio(1);
;     bf16x8 a[4];
; #pragma unroll
;     for (int mi = 0; mi < 4; ++mi) a[mi] = *(const bf16x8*)(Ws + (wf * 64 + mi * 16 + lr) * LST + lq * 8);
; #pragma unroll
;     for (int ni = 0; ni < NI; ++ni) {
;       const bf16x8 b = *(const bf16x8*)(Xs + (wt * (NI * 16) + ni * 16 + lr) * LST + lq * 8);
; #pragma unroll
;       for (int mi = 0; mi < 4; ++mi) acc[mi][ni] = mfma16(a[mi], b, acc[mi][ni]);
;     }
;     __builtin_amdgcn_sched_group_barrier(0x100, 6, 0);
; #pragma unroll
;     for (int ni = 0; ni < NI; ++ni) { __builtin_amdgcn_sched_group_barrier(0x008, 4, 0); if (ni + 2 < NI) __builtin_amdgcn_sched_group_barrier(0x100, 1, 0); }
;     __builtin_amdgcn_s_setprio(0);
;     if (it + 1 < nk) lstore((it + 1) & 1);
;     if (it + 2 < nk) gload(it + 2);
;     __syncthreads();
;   }
	v_mfma_f32_16x16x32_bf16 v[132:135], v[168:171], v[188:191], v[132:135]
	v_mfma_f32_16x16x32_bf16 v[108:111], v[172:175], v[188:191], v[108:111]
	v_mfma_f32_16x16x32_bf16 v[76:79], v[180:183], v[188:191], v[76:79]
	v_mfma_f32_16x16x32_bf16 v[40:43], v[184:187], v[188:191], v[40:43]
	ds_read_b128 v[188:191], v152 offset:56832
	ds_write_b128 v230, v[212:215] offset:12384
	global_load_dwordx4 v[212:215], v156, s[100:101] offset:2112
	s_waitcnt lgkmcnt(3)
	v_mfma_f32_16x16x32_bf16 v[124:127], v[168:171], v[176:179], v[124:127]
	v_mfma_f32_16x16x32_bf16 v[96:99], v[172:175], v[176:179], v[96:99]
	v_mfma_f32_16x16x32_bf16 v[64:67], v[180:183], v[176:179], v[64:67]
	v_mfma_f32_16x16x32_bf16 v[12:15], v[184:187], v[176:179], v[12:15]
	ds_read_b128 v[176:179], v152 offset:58368
	ds_write_b128 v230, v[220:223] offset:12480
	global_load_dwordx4 v[220:223], v156, s[100:101] offset:2176
	s_waitcnt lgkmcnt(3)
	v_mfma_f32_16x16x32_bf16 v[116:119], v[168:171], v[188:191], v[116:119]
	v_mfma_f32_16x16x32_bf16 v[84:87], v[172:175], v[188:191], v[84:87]
	v_mfma_f32_16x16x32_bf16 v[56:59], v[180:183], v[188:191], v[56:59]
	v_mfma_f32_16x16x32_bf16 v[8:11], v[184:187], v[188:191], v[8:11]
	ds_read_b128 v[188:191], v152 offset:59904
	ds_write_b128 v230, v[224:227] offset:12576
	global_load_dwordx4 v[224:227], v156, s[100:101] offset:2240
	s_waitcnt lgkmcnt(3)
	v_mfma_f32_16x16x32_bf16 v[104:107], v[168:171], v[176:179], v[104:107]
	v_mfma_f32_16x16x32_bf16 v[72:75], v[172:175], v[176:179], v[72:75]
	v_mfma_f32_16x16x32_bf16 v[52:55], v[180:183], v[176:179], v[52:55]
	v_mfma_f32_16x16x32_bf16 v[4:7], v[184:187], v[176:179], v[4:7]
	s_add_u32 s98, s98, s18
	s_addc_u32 s99, s99, s19
	s_add_u32 s100, s100, s10
	s_addc_u32 s101, s101, s11
	s_add_i32 s36, s36, 2
	s_waitcnt lgkmcnt(1)
	v_mfma_f32_16x16x32_bf16 v[92:95], v[168:171], v[188:191], v[92:95]
	v_mfma_f32_16x16x32_bf16 v[60:63], v[172:175], v[188:191], v[60:63]
	v_mfma_f32_16x16x32_bf16 v[48:51], v[180:183], v[188:191], v[48:51]
	v_mfma_f32_16x16x32_bf16 v[0:3], v[184:187], v[188:191], v[0:3]
	s_setprio 0
	s_cmp_lg_u32 s36, 29
	s_waitcnt lgkmcnt(0)
	s_barrier
	s_cbranch_scc1 .LBB0_812
	s_setprio 1
	ds_read_b128 v[168:171], v228 offset:0
	ds_read_b128 v[172:175], v228 offset:1536
	ds_read_b128 v[180:183], v228 offset:3072
	ds_read_b128 v[184:187], v228 offset:4608
	ds_read_b128 v[176:179], v152 offset:12288
	ds_read_b128 v[188:191], v152 offset:13824
	s_waitcnt lgkmcnt(1)
	v_mfma_f32_16x16x32_bf16 v[148:151], v[168:171], v[176:179], v[148:151]
	v_mfma_f32_16x16x32_bf16 v[136:139], v[172:175], v[176:179], v[136:139]
	v_mfma_f32_16x16x32_bf16 v[112:115], v[180:183], v[176:179], v[112:115]
	v_mfma_f32_16x16x32_bf16 v[80:83], v[184:187], v[176:179], v[80:83]
	ds_read_b128 v[176:179], v152 offset:15360
	s_waitcnt vmcnt(6)
	ds_write_b128 v229, v[20:23] offset:36864
	s_waitcnt lgkmcnt(2)
	v_mfma_f32_16x16x32_bf16 v[144:147], v[168:171], v[188:191], v[144:147]
	v_mfma_f32_16x16x32_bf16 v[128:131], v[172:175], v[188:191], v[128:131]
	v_mfma_f32_16x16x32_bf16 v[100:103], v[180:183], v[188:191], v[100:103]
	v_mfma_f32_16x16x32_bf16 v[68:71], v[184:187], v[188:191], v[68:71]
	ds_read_b128 v[188:191], v152 offset:16896
	ds_write_b128 v229, v[16:19] offset:36960
	global_load_dwordx4 v[20:23], v154, s[98:99]
	global_load_dwordx4 v[16:19], v154, s[98:99] offset:64
	s_waitcnt lgkmcnt(3)
	v_mfma_f32_16x16x32_bf16 v[140:143], v[168:171], v[176:179], v[140:143]
	v_mfma_f32_16x16x32_bf16 v[120:123], v[172:175], v[176:179], v[120:123]
	v_mfma_f32_16x16x32_bf16 v[88:91], v[180:183], v[176:179], v[88:91]
	v_mfma_f32_16x16x32_bf16 v[44:47], v[184:187], v[176:179], v[44:47]
	ds_read_b128 v[176:179], v152 offset:18432
	ds_write_b128 v230, v[36:39] offset:49152
	global_load_dwordx4 v[36:39], v156, s[100:101] offset:2048
	s_waitcnt lgkmcnt(3)
	v_mfma_f32_16x16x32_bf16 v[132:135], v[168:171], v[188:191], v[132:135]
	v_mfma_f32_16x16x32_bf16 v[108:111], v[172:175], v[188:191], v[108:111]
	v_mfma_f32_16x16x32_bf16 v[76:79], v[180:183], v[188:191], v[76:79]
	v_mfma_f32_16x16x32_bf16 v[40:43], v[184:187], v[188:191], v[40:43]
	ds_read_b128 v[188:191], v152 offset:19968
	ds_write_b128 v230, v[32:35] offset:49248
	global_load_dwordx4 v[32:35], v156, s[100:101] offset:2112
	s_waitcnt lgkmcnt(3)
	v_mfma_f32_16x16x32_bf16 v[124:127], v[168:171], v[176:179], v[124:127]
	v_mfma_f32_16x16x32_bf16 v[96:99], v[172:175], v[176:179], v[96:99]
	v_mfma_f32_16x16x32_bf16 v[64:67], v[180:183], v[176:179], v[64:67]
	v_mfma_f32_16x16x32_bf16 v[12:15], v[184:187], v[176:179], v[12:15]
	ds_read_b128 v[176:179], v152 offset:21504
	ds_write_b128 v230, v[28:31] offset:49344
	global_load_dwordx4 v[28:31], v156, s[100:101] offset:2176
	s_waitcnt lgkmcnt(3)
	v_mfma_f32_16x16x32_bf16 v[116:119], v[168:171], v[188:191], v[116:119]
	v_mfma_f32_16x16x32_bf16 v[84:87], v[172:175], v[188:191], v[84:87]
	v_mfma_f32_16x16x32_bf16 v[56:59], v[180:183], v[188:191], v[56:59]
	v_mfma_f32_16x16x32_bf16 v[8:11], v[184:187], v[188:191], v[8:11]
	ds_read_b128 v[188:191], v152 offset:23040
	ds_write_b128 v230, v[24:27] offset:49440
	global_load_dwordx4 v[24:27], v156, s[100:101] offset:2240
	s_waitcnt lgkmcnt(3)
	v_mfma_f32_16x16x32_bf16 v[104:107], v[168:171], v[176:179], v[104:107]
	v_mfma_f32_16x16x32_bf16 v[72:75], v[172:175], v[176:179], v[72:75]
	v_mfma_f32_16x16x32_bf16 v[52:55], v[180:183], v[176:179], v[52:55]
	v_mfma_f32_16x16x32_bf16 v[4:7], v[184:187], v[176:179], v[4:7]
	s_add_u32 s98, s98, s18
	s_addc_u32 s99, s99, s19
	s_add_u32 s100, s100, s10
	s_addc_u32 s101, s101, s11
	s_waitcnt lgkmcnt(1)
	v_mfma_f32_16x16x32_bf16 v[92:95], v[168:171], v[188:191], v[92:95]
	v_mfma_f32_16x16x32_bf16 v[60:63], v[172:175], v[188:191], v[60:63]
	v_mfma_f32_16x16x32_bf16 v[48:51], v[180:183], v[188:191], v[48:51]
	v_mfma_f32_16x16x32_bf16 v[0:3], v[184:187], v[188:191], v[0:3]
	s_setprio 0
	s_waitcnt lgkmcnt(0)
	s_barrier
; DI f32x4 mfma16(bf16x8 a, bf16x8 b, f32x4 c) { return __builtin_amdgcn_mfma_f32_16x16x32_bf16(a, b, c, 0, 0, 0); }
; template <int NI, class XL, class EP>
; DI void gemm_tile(const u16* __restrict__ W, int ldw, int f0, int t0, int K, XL xl, EP ep, unsigned char* smem) {
;     ...
;   for (int it = 0; it < nk; ++it) {
;     const u16* Ws = S0 + (it & 1) * BUF; const u16* Xs = Ws + 128 * LST;
;     __builtin_amdgcn_s_setprio(1);
;     bf16x8 a[4];
; #pragma unroll
;     for (int mi = 0; mi < 4; ++mi) a[mi] = *(const bf16x8*)(Ws + (wf * 64 + mi * 16 + lr) * LST + lq * 8);
; #pragma unroll
;     for (int ni = 0; ni < NI; ++ni) {
;       const bf16x8 b = *(const bf16x8*)(Xs + (wt * (NI * 16) + ni * 16 + lr) * LST + lq * 8);
; #pragma unroll
;       for (int mi = 0; mi < 4; ++mi) acc[mi][ni] = mfma16(a[mi], b, acc[mi][ni]);
;     }
;     __builtin_amdgcn_sched_group_barrier(0x100, 6, 0);
; #pragma unroll
;     for (int ni = 0; ni < NI; ++ni) { __builtin_amdgcn_sched_group_barrier(0x008, 4, 0); if (ni + 2 < NI) __builtin_amdgcn_sched_group_barrier(0x100, 1, 0); }
;     __builtin_amdgcn_s_setprio(0);
;     if (it + 1 < nk) lstore((it + 1) & 1);
;     if (it + 2 < nk) gload(it + 2);
;     __syncthreads();
;   }
	s_setprio 1
	ds_read_b128 v[168:171], v228 offset:36864
	ds_read_b128 v[172:175], v228 offset:38400
	ds_read_b128 v[180:183], v228 offset:39936
	ds_read_b128 v[184:187], v228 offset:41472
	ds_read_b128 v[176:179], v152 offset:49152
	ds_read_b128 v[188:191], v152 offset:50688
	s_waitcnt lgkmcnt(1)
	v_mfma_f32_16x16x32_bf16 v[148:151], v[168:171], v[176:179], v[148:151]
	v_mfma_f32_16x16x32_bf16 v[136:139], v[172:175], v[176:179], v[136:139]
	v_mfma_f32_16x16x32_bf16 v[112:115], v[180:183], v[176:179], v[112:115]
	v_mfma_f32_16x16x32_bf16 v[80:83], v[184:187], v[176:179], v[80:83]
	ds_read_b128 v[176:179], v152 offset:52224
	s_waitcnt vmcnt(6)
	ds_write_b128 v229, v[200:203] offset:0
	s_waitcnt lgkmcnt(2)
	v_mfma_f32_16x16x32_bf16 v[144:147], v[168:171], v[188:191], v[144:147]
	v_mfma_f32_16x16x32_bf16 v[128:131], v[172:175], v[188:191], v[128:131]
	v_mfma_f32_16x16x32_bf16 v[100:103], v[180:183], v[188:191], v[100:103]
	v_mfma_f32_16x16x32_bf16 v[68:71], v[184:187], v[188:191], v[68:71]
	ds_read_b128 v[188:191], v152 offset:53760
	ds_write_b128 v229, v[204:207] offset:96
	s_waitcnt lgkmcnt(3)
	v_mfma_f32_16x16x32_bf16 v[140:143], v[168:171], v[176:179], v[140:143]
	v_mfma_f32_16x16x32_bf16 v[120:123], v[172:175], v[176:179], v[120:123]
	v_mfma_f32_16x16x32_bf16 v[88:91], v[180:183], v[176:179], v[88:91]
	v_mfma_f32_16x16x32_bf16 v[44:47], v[184:187], v[176:179], v[44:47]
	ds_read_b128 v[176:179], v152 offset:55296
	ds_write_b128 v230, v[208:211] offset:12288
	s_waitcnt lgkmcnt(3)
	v_mfma_f32_16x16x32_bf16 v[132:135], v[168:171], v[188:191], v[132:135]
	v_mfma_f32_16x16x32_bf16 v[108:111], v[172:175], v[188:191], v[108:111]
	v_mfma_f32_16x16x32_bf16 v[76:79], v[180:183], v[188:191], v[76:79]
	v_mfma_f32_16x16x32_bf16 v[40:43], v[184:187], v[188:191], v[40:43]
	ds_read_b128 v[188:191], v152 offset:56832
	ds_write_b128 v230, v[212:215] offset:12384
	s_waitcnt lgkmcnt(3)
	v_mfma_f32_16x16x32_bf16 v[124:127], v[168:171], v[176:179], v[124:127]
	v_mfma_f32_16x16x32_bf16 v[96:99], v[172:175], v[176:179], v[96:99]
	v_mfma_f32_16x16x32_bf16 v[64:67], v[180:183], v[176:179], v[64:67]
	v_mfma_f32_16x16x32_bf16 v[12:15], v[184:187], v[176:179], v[12:15]
	ds_read_b128 v[176:179], v152 offset:58368
	ds_write_b128 v230, v[220:223] offset:12480
	s_waitcnt lgkmcnt(3)
	v_mfma_f32_16x16x32_bf16 v[116:119], v[168:171], v[188:191], v[116:119]
	v_mfma_f32_16x16x32_bf16 v[84:87], v[172:175], v[188:191], v[84:87]
	v_mfma_f32_16x16x32_bf16 v[56:59], v[180:183], v[188:191], v[56:59]
	v_mfma_f32_16x16x32_bf16 v[8:11], v[184:187], v[188:191], v[8:11]
	ds_read_b128 v[188:191], v152 offset:59904
	ds_write_b128 v230, v[224:227] offset:12576
	s_waitcnt lgkmcnt(3)
	v_mfma_f32_16x16x32_bf16 v[104:107], v[168:171], v[176:179], v[104:107]
	v_mfma_f32_16x16x32_bf16 v[72:75], v[172:175], v[176:179], v[72:75]
	v_mfma_f32_16x16x32_bf16 v[52:55], v[180:183], v[176:179], v[52:55]
	v_mfma_f32_16x16x32_bf16 v[4:7], v[184:187], v[176:179], v[4:7]
	s_add_i32 s36, s36, 2
	s_waitcnt lgkmcnt(1)
	v_mfma_f32_16x16x32_bf16 v[92:95], v[168:171], v[188:191], v[92:95]
	v_mfma_f32_16x16x32_bf16 v[60:63], v[172:175], v[188:191], v[60:63]
	v_mfma_f32_16x16x32_bf16 v[48:51], v[180:183], v[188:191], v[48:51]
	v_mfma_f32_16x16x32_bf16 v[0:3], v[184:187], v[188:191], v[0:3]
	s_setprio 0
	s_waitcnt lgkmcnt(0)
	s_barrier
	s_setprio 1
	v_lshl_add_u32 v152, v167, 1, v164
	ds_read_b128 v[154:157], v152
	v_lshl_add_u32 v161, v165, 1, v164
	ds_read_b128 v[164:167], v152 offset:1536
	ds_read_b128 v[172:175], v152 offset:3072
	ds_read_b128 v[176:179], v152 offset:4608
	ds_read_b128 v[168:171], v161 offset:12288
	ds_read_b128 v[180:183], v161 offset:13824
	s_waitcnt lgkmcnt(1)
	v_mfma_f32_16x16x32_bf16 v[148:151], v[154:157], v[168:171], v[148:151]
	v_mfma_f32_16x16x32_bf16 v[136:139], v[164:167], v[168:171], v[136:139]
	v_mfma_f32_16x16x32_bf16 v[112:115], v[172:175], v[168:171], v[112:115]
	v_mfma_f32_16x16x32_bf16 v[80:83], v[176:179], v[168:171], v[80:83]
	ds_read_b128 v[168:171], v161 offset:15360
	s_waitcnt vmcnt(5)
	ds_write_b128 v162, v[20:23] offset:36864
	s_waitcnt lgkmcnt(2)
	v_mfma_f32_16x16x32_bf16 v[144:147], v[154:157], v[180:183], v[144:147]
	v_mfma_f32_16x16x32_bf16 v[128:131], v[164:167], v[180:183], v[128:131]
	v_mfma_f32_16x16x32_bf16 v[100:103], v[172:175], v[180:183], v[100:103]
	v_mfma_f32_16x16x32_bf16 v[68:71], v[176:179], v[180:183], v[68:71]
	ds_read_b128 v[180:183], v161 offset:16896
	s_waitcnt vmcnt(4)
	ds_write_b128 v162, v[16:19] offset:36960
	s_waitcnt lgkmcnt(3)
	v_mfma_f32_16x16x32_bf16 v[140:143], v[154:157], v[168:171], v[140:143]
	v_mfma_f32_16x16x32_bf16 v[120:123], v[164:167], v[168:171], v[120:123]
	v_mfma_f32_16x16x32_bf16 v[184:187], v[172:175], v[168:171], v[88:91]
	v_mfma_f32_16x16x32_bf16 v[44:47], v[176:179], v[168:171], v[44:47]
	s_nop 1
	ds_read_b128 v[88:91], v161 offset:18432
	s_waitcnt vmcnt(3)
	ds_write_b128 v163, v[36:39] offset:49152
	s_waitcnt lgkmcnt(3)
	v_mfma_f32_16x16x32_bf16 v[132:135], v[154:157], v[180:183], v[132:135]
	v_mfma_f32_16x16x32_bf16 v[168:171], v[164:167], v[180:183], v[108:111]
	v_mfma_f32_16x16x32_bf16 v[188:191], v[172:175], v[180:183], v[76:79]
	v_mfma_f32_16x16x32_bf16 v[180:183], v[176:179], v[180:183], v[40:43]
	s_nop 2
	ds_read_b128 v[40:43], v161 offset:19968
	s_waitcnt vmcnt(2)
	ds_write_b128 v163, v[32:35] offset:49248
	s_waitcnt lgkmcnt(3)
	v_mfma_f32_16x16x32_bf16 v[124:127], v[154:157], v[88:91], v[124:127]
	v_mfma_f32_16x16x32_bf16 v[192:195], v[164:167], v[88:91], v[96:99]
	v_mfma_f32_16x16x32_bf16 v[196:199], v[172:175], v[88:91], v[64:67]
	v_mfma_f32_16x16x32_bf16 v[200:203], v[176:179], v[88:91], v[12:15]
	s_nop 2
	ds_read_b128 v[12:15], v161 offset:21504
	s_waitcnt vmcnt(1)
	ds_write_b128 v163, v[28:31] offset:49344
	s_waitcnt lgkmcnt(3)
	v_mfma_f32_16x16x32_bf16 v[116:119], v[154:157], v[40:43], v[116:119]
	v_mfma_f32_16x16x32_bf16 v[204:207], v[164:167], v[40:43], v[84:87]
	v_mfma_f32_16x16x32_bf16 v[56:59], v[172:175], v[40:43], v[56:59]
	v_mfma_f32_16x16x32_bf16 v[208:211], v[176:179], v[40:43], v[8:11]
	s_nop 2
	ds_read_b128 v[8:11], v161 offset:23040
	s_waitcnt vmcnt(0)
	ds_write_b128 v163, v[24:27] offset:49440
	s_waitcnt lgkmcnt(3)
	v_mfma_f32_16x16x32_bf16 v[212:215], v[154:157], v[12:15], v[104:107]
	v_mfma_f32_16x16x32_bf16 v[72:75], v[164:167], v[12:15], v[72:75]
	v_mfma_f32_16x16x32_bf16 v[220:223], v[172:175], v[12:15], v[52:55]
	v_mfma_f32_16x16x32_bf16 v[224:227], v[176:179], v[12:15], v[4:7]
	s_waitcnt lgkmcnt(1)
	v_mfma_f32_16x16x32_bf16 v[154:157], v[154:157], v[8:11], v[92:95]
	v_mfma_f32_16x16x32_bf16 v[60:63], v[164:167], v[8:11], v[60:63]
	v_mfma_f32_16x16x32_bf16 v[164:167], v[172:175], v[8:11], v[48:51]
	v_mfma_f32_16x16x32_bf16 v[172:175], v[176:179], v[8:11], v[0:3]
	s_setprio 0
	s_waitcnt lgkmcnt(0)
	s_barrier
; DI void store4(u16* dst, f32x4 v) { uint2 w; w.x = cvtpk(v[0], v[1]); w.y = cvtpk(v[2], v[3]); *(uint2*)dst = w; }
; DI f32x4 mfma16(bf16x8 a, bf16x8 b, f32x4 c) { return __builtin_amdgcn_mfma_f32_16x16x32_bf16(a, b, c, 0, 0, 0); }
; template <int NI, class XL, class EP>
; DI void gemm_tile(const u16* __restrict__ W, int ldw, int f0, int t0, int K, XL xl, EP ep, unsigned char* smem) {
;     ...
;     for (int mi = 0; mi < 4; ++mi) a[mi] = *(const bf16x8*)(Ws + (wf * 64 + mi * 16 + lr) * LST + lq * 8);
; #pragma unroll
;     for (int ni = 0; ni < NI; ++ni) {
;       const bf16x8 b = *(const bf16x8*)(Xs + (wt * (NI * 16) + ni * 16 + lr) * LST + lq * 8);
; #pragma unroll
;       for (int mi = 0; mi < 4; ++mi) acc[mi][ni] = mfma16(a[mi], b, acc[mi][ni]);
;     }
;     __builtin_amdgcn_sched_group_barrier(0x100, 6, 0);
; #pragma unroll
;     for (int ni = 0; ni < NI; ++ni) { __builtin_amdgcn_sched_group_barrier(0x008, 4, 0); if (ni + 2 < NI) __builtin_amdgcn_sched_group_barrier(0x100, 1, 0); }
;     __builtin_amdgcn_s_setprio(0);
; DI void phase6(const Params& p, const Sched& sched, unsigned char* smem) {
;     ...
;       const int b = tb >> 11;
;       __syncthreads();
; #pragma unroll
;       for (int mi = 0; mi < 4; ++mi) {
;         const int f = fb + mi * 16 + lq * 4; const float4 gm = *(const float4*)(mod + (size_t)b * 6144 + 2048 + f);
; #pragma unroll
;         for (int ni = 0; ni < 8; ++ni) {
;           const f32x4 o = {gm.x * acc[mi][ni][0], gm.y * acc[mi][ni][1], gm.z * acc[mi][ni][2], gm.w * acc[mi][ni][3]};
;           store4(Ls + (wt * 128 + ni * 16 + lr) * EST + wf * 64 + mi * 16 + lq * 4, o);
;         }
;       }
	s_lshl_b32 s34, s34, 7
	s_setprio 1
	ds_read_b128 v[28:31], v152 offset:36864
	ds_read_b128 v[176:179], v152 offset:38400
	ds_read_b128 v[228:231], v152 offset:39936
	ds_read_b128 v[232:235], v152 offset:41472
	ds_read_b128 v[0:3], v161 offset:49152
	ds_read_b128 v[4:7], v161 offset:50688
	s_waitcnt lgkmcnt(1)
	v_mfma_f32_16x16x32_bf16 v[88:91], v[28:31], v[0:3], v[148:151]
	v_mfma_f32_16x16x32_bf16 v[64:67], v[176:179], v[0:3], v[136:139]
	v_mfma_f32_16x16x32_bf16 v[32:35], v[228:231], v[0:3], v[112:115]
	v_mfma_f32_16x16x32_bf16 v[0:3], v[232:235], v[0:3], v[80:83]
	ds_read_b128 v[8:11], v161 offset:52224
	s_waitcnt lgkmcnt(1)
	v_mfma_f32_16x16x32_bf16 v[96:99], v[28:31], v[4:7], v[144:147]
	v_mfma_f32_16x16x32_bf16 v[76:79], v[176:179], v[4:7], v[128:131]
	v_mfma_f32_16x16x32_bf16 v[36:39], v[228:231], v[4:7], v[100:103]
	v_mfma_f32_16x16x32_bf16 v[4:7], v[232:235], v[4:7], v[68:71]
	ds_read_b128 v[12:15], v161 offset:53760
	s_waitcnt lgkmcnt(1)
	v_mfma_f32_16x16x32_bf16 v[104:107], v[28:31], v[8:11], v[140:143]
	v_mfma_f32_16x16x32_bf16 v[84:87], v[176:179], v[8:11], v[120:123]
	v_mfma_f32_16x16x32_bf16 v[40:43], v[228:231], v[8:11], v[184:187]
	v_mfma_f32_16x16x32_bf16 v[8:11], v[232:235], v[8:11], v[44:47]
	ds_read_b128 v[16:19], v161 offset:55296
	s_waitcnt lgkmcnt(1)
	v_mfma_f32_16x16x32_bf16 v[108:111], v[28:31], v[12:15], v[132:135]
	v_mfma_f32_16x16x32_bf16 v[92:95], v[176:179], v[12:15], v[168:171]
	v_mfma_f32_16x16x32_bf16 v[44:47], v[228:231], v[12:15], v[188:191]
	v_mfma_f32_16x16x32_bf16 v[12:15], v[232:235], v[12:15], v[180:183]
	ds_read_b128 v[20:23], v161 offset:56832
	s_waitcnt lgkmcnt(1)
	v_mfma_f32_16x16x32_bf16 v[112:115], v[28:31], v[16:19], v[124:127]
	v_mfma_f32_16x16x32_bf16 v[100:103], v[176:179], v[16:19], v[192:195]
	v_mfma_f32_16x16x32_bf16 v[48:51], v[228:231], v[16:19], v[196:199]
	v_mfma_f32_16x16x32_bf16 v[16:19], v[232:235], v[16:19], v[200:203]
	ds_read_b128 v[24:27], v161 offset:58368
	s_waitcnt lgkmcnt(1)
	v_mfma_f32_16x16x32_bf16 v[116:119], v[28:31], v[20:23], v[116:119]
	v_mfma_f32_16x16x32_bf16 v[68:71], v[176:179], v[20:23], v[204:207]
	v_mfma_f32_16x16x32_bf16 v[52:55], v[228:231], v[20:23], v[56:59]
	v_mfma_f32_16x16x32_bf16 v[20:23], v[232:235], v[20:23], v[208:211]
	ds_read_b128 v[128:131], v161 offset:59904
	s_waitcnt lgkmcnt(1)
	v_mfma_f32_16x16x32_bf16 v[120:123], v[28:31], v[24:27], v[212:215]
	v_mfma_f32_16x16x32_bf16 v[80:83], v[176:179], v[24:27], v[72:75]
	v_mfma_f32_16x16x32_bf16 v[56:59], v[228:231], v[24:27], v[220:223]
	v_mfma_f32_16x16x32_bf16 v[24:27], v[232:235], v[24:27], v[224:227]
	s_waitcnt lgkmcnt(0)
	v_mfma_f32_16x16x32_bf16 v[124:127], v[28:31], v[128:131], v[154:157]
	v_mfma_f32_16x16x32_bf16 v[72:75], v[176:179], v[128:131], v[60:63]
	v_mfma_f32_16x16x32_bf16 v[60:63], v[228:231], v[128:131], v[164:167]
	v_mfma_f32_16x16x32_bf16 v[28:31], v[232:235], v[128:131], v[172:175]
	s_setprio 0
	s_ashr_i32 s35, s35, 3
	v_add_u32_e32 v128, s34, v160
	s_mul_hi_i32 s37, s35, 0x6000
	s_mulk_i32 s35, 0x6000
	v_lshl_or_b32 v128, v158, 2, v128
	s_add_u32 s36, s72, s35
	s_addc_u32 s37, s73, s37
	v_ashrrev_i32_e32 v129, 31, v128
	v_lshl_add_u64 v[128:129], v[128:129], 2, s[36:37]
	v_add_co_u32_e32 v140, vcc, s26, v128
	v_mul_u32_u24_e32 v138, 0x88, v159
	s_nop 0
	v_addc_co_u32_e32 v141, vcc, 0, v129, vcc
	v_lshlrev_b32_e32 v136, 1, v160
	v_lshlrev_b32_e32 v137, 3, v158
	v_lshlrev_b32_e32 v138, 1, v138
	s_barrier
	global_load_dwordx4 v[128:131], v[140:141], off
	global_load_dwordx4 v[132:135], v[140:141], off offset:64
	v_add3_u32 v144, v136, v137, v138
	global_load_dwordx4 v[136:139], v[140:141], off offset:128
	v_add_u32_e32 v145, 0x1000, v144
	global_load_dwordx4 v[140:143], v[140:141], off offset:192
	v_add_u32_e32 v146, 0x2000, v144
	v_add_u32_e32 v147, 0x3000, v144
	v_add_u32_e32 v148, 0x4000, v144
	s_add_i32 s31, s31, s78
	s_add_i32 s30, s30, s78
	s_cmp_gt_i32 s31, 63
	s_waitcnt vmcnt(3)
	v_pk_mul_f32 v[88:89], v[88:89], v[128:129]
	v_pk_mul_f32 v[90:91], v[90:91], v[130:131]
	v_pk_mul_f32 v[96:97], v[96:97], v[128:129]
	s_waitcnt vmcnt(1)
	v_pk_mul_f32 v[32:33], v[32:33], v[136:137]
	v_pk_mul_f32 v[34:35], v[34:35], v[138:139]
	s_waitcnt vmcnt(0)
	v_pk_mul_f32 v[0:1], v[0:1], v[140:141]
	v_pk_mul_f32 v[2:3], v[2:3], v[142:143]
	v_cvt_pk_bf16_f32 v32, v32, v33
	v_cvt_pk_bf16_f32 v33, v34, v35
	v_cvt_pk_bf16_f32 v0, v0, v1
	v_cvt_pk_bf16_f32 v1, v2, v3
	v_pk_mul_f32 v[34:35], v[36:37], v[136:137]
	v_pk_mul_f32 v[36:37], v[38:39], v[138:139]
	ds_write2_b64 v144, v[32:33], v[0:1] offset0:8 offset1:12
	v_pk_mul_f32 v[0:1], v[4:5], v[140:141]
	v_pk_mul_f32 v[2:3], v[6:7], v[142:143]
	v_cvt_pk_bf16_f32 v34, v34, v35
	v_cvt_pk_bf16_f32 v35, v36, v37
	v_cvt_pk_bf16_f32 v0, v0, v1
	v_cvt_pk_bf16_f32 v1, v2, v3
	v_pk_mul_f32 v[36:37], v[40:41], v[136:137]
	v_pk_mul_f32 v[38:39], v[42:43], v[138:139]
	ds_write2_b64 v145, v[34:35], v[0:1] offset0:40 offset1:44
	v_pk_mul_f32 v[0:1], v[8:9], v[140:141]
	v_pk_mul_f32 v[2:3], v[10:11], v[142:143]
	v_cvt_pk_bf16_f32 v36, v36, v37
	v_cvt_pk_bf16_f32 v37, v38, v39
	v_cvt_pk_bf16_f32 v0, v0, v1
	v_cvt_pk_bf16_f32 v1, v2, v3
	v_pk_mul_f32 v[38:39], v[44:45], v[136:137]
	v_pk_mul_f32 v[40:41], v[46:47], v[138:139]
	ds_write2_b64 v146, v[36:37], v[0:1] offset0:72 offset1:76
	v_pk_mul_f32 v[0:1], v[12:13], v[140:141]
	v_pk_mul_f32 v[2:3], v[14:15], v[142:143]
	v_cvt_pk_bf16_f32 v38, v38, v39
	v_cvt_pk_bf16_f32 v39, v40, v41
	v_cvt_pk_bf16_f32 v0, v0, v1
	v_cvt_pk_bf16_f32 v1, v2, v3
	v_pk_mul_f32 v[98:99], v[98:99], v[130:131]
	v_pk_mul_f32 v[64:65], v[64:65], v[132:133]
	v_pk_mul_f32 v[66:67], v[66:67], v[134:135]
	v_pk_mul_f32 v[76:77], v[76:77], v[132:133]
; DI void store4(u16* dst, f32x4 v) { uint2 w; w.x = cvtpk(v[0], v[1]); w.y = cvtpk(v[2], v[3]); *(uint2*)dst = w; }
; DI void phase6(const Params& p, const Sched& sched, unsigned char* smem) {
;     ...
; #pragma unroll
;       for (int mi = 0; mi < 4; ++mi) {
;         const int f = fb + mi * 16 + lq * 4; const float4 gm = *(const float4*)(mod + (size_t)b * 6144 + 2048 + f);
; #pragma unroll
;         for (int ni = 0; ni < 8; ++ni) {
;           const f32x4 o = {gm.x * acc[mi][ni][0], gm.y * acc[mi][ni][1], gm.z * acc[mi][ni][2], gm.w * acc[mi][ni][3]};
;           store4(Ls + (wt * 128 + ni * 16 + lr) * EST + wf * 64 + mi * 16 + lq * 4, o);
;         }
;       }
;       __syncthreads();
	v_pk_mul_f32 v[78:79], v[78:79], v[134:135]
	v_pk_mul_f32 v[40:41], v[48:49], v[136:137]
	v_pk_mul_f32 v[42:43], v[50:51], v[138:139]
	ds_write2_b64 v147, v[38:39], v[0:1] offset0:104 offset1:108
	v_pk_mul_f32 v[0:1], v[16:17], v[140:141]
	v_pk_mul_f32 v[2:3], v[18:19], v[142:143]
	v_cvt_pk_bf16_f32 v88, v88, v89
	v_cvt_pk_bf16_f32 v89, v90, v91
	v_cvt_pk_bf16_f32 v90, v96, v97
	v_cvt_pk_bf16_f32 v91, v98, v99
	v_cvt_pk_bf16_f32 v64, v64, v65
	v_cvt_pk_bf16_f32 v65, v66, v67
	v_cvt_pk_bf16_f32 v66, v76, v77
	v_cvt_pk_bf16_f32 v67, v78, v79
	v_cvt_pk_bf16_f32 v40, v40, v41
	v_cvt_pk_bf16_f32 v41, v42, v43
	v_cvt_pk_bf16_f32 v0, v0, v1
	v_cvt_pk_bf16_f32 v1, v2, v3
	v_pk_mul_f32 v[106:107], v[106:107], v[130:131]
	v_pk_mul_f32 v[116:117], v[116:117], v[128:129]
	v_pk_mul_f32 v[118:119], v[118:119], v[130:131]
	ds_write2_b64 v144, v[88:89], v[64:65] offset1:4
	ds_write2_b64 v145, v[90:91], v[66:67] offset0:32 offset1:36
	v_pk_mul_f32 v[64:65], v[68:69], v[132:133]
	v_pk_mul_f32 v[66:67], v[70:71], v[134:135]
	v_pk_mul_f32 v[42:43], v[52:53], v[136:137]
	v_pk_mul_f32 v[44:45], v[54:55], v[138:139]
	ds_write2_b64 v148, v[40:41], v[0:1] offset0:136 offset1:140
	v_pk_mul_f32 v[0:1], v[20:21], v[140:141]
	v_pk_mul_f32 v[2:3], v[22:23], v[142:143]
	v_cvt_pk_bf16_f32 v97, v106, v107
	v_cvt_pk_bf16_f32 v106, v116, v117
	v_cvt_pk_bf16_f32 v107, v118, v119
	v_cvt_pk_bf16_f32 v64, v64, v65
	v_cvt_pk_bf16_f32 v65, v66, v67
	v_add_u32_e32 v68, 0x5000, v144
	v_cvt_pk_bf16_f32 v42, v42, v43
	v_cvt_pk_bf16_f32 v43, v44, v45
	v_cvt_pk_bf16_f32 v0, v0, v1
	v_cvt_pk_bf16_f32 v1, v2, v3
	v_pk_mul_f32 v[108:109], v[108:109], v[128:129]
	v_pk_mul_f32 v[120:121], v[120:121], v[128:129]
	v_pk_mul_f32 v[122:123], v[122:123], v[130:131]
	ds_write2_b64 v68, v[106:107], v[64:65] offset0:160 offset1:164
	v_pk_mul_f32 v[64:65], v[80:81], v[132:133]
	v_pk_mul_f32 v[66:67], v[82:83], v[134:135]
	v_pk_mul_f32 v[44:45], v[56:57], v[136:137]
	v_pk_mul_f32 v[46:47], v[58:59], v[138:139]
	ds_write2_b64 v68, v[42:43], v[0:1] offset0:168 offset1:172
	v_pk_mul_f32 v[0:1], v[24:25], v[140:141]
	v_pk_mul_f32 v[2:3], v[26:27], v[142:143]
	v_cvt_pk_bf16_f32 v98, v108, v109
	v_cvt_pk_bf16_f32 v108, v120, v121
	v_cvt_pk_bf16_f32 v109, v122, v123
	v_cvt_pk_bf16_f32 v64, v64, v65
	v_cvt_pk_bf16_f32 v65, v66, v67
	v_add_u32_e32 v69, 0x6000, v144
	v_cvt_pk_bf16_f32 v44, v44, v45
	v_cvt_pk_bf16_f32 v45, v46, v47
	v_cvt_pk_bf16_f32 v0, v0, v1
	v_cvt_pk_bf16_f32 v1, v2, v3
	v_pk_mul_f32 v[104:105], v[104:105], v[128:129]
	v_pk_mul_f32 v[110:111], v[110:111], v[130:131]
	v_pk_mul_f32 v[112:113], v[112:113], v[128:129]
	v_pk_mul_f32 v[114:115], v[114:115], v[130:131]
	v_pk_mul_f32 v[124:125], v[124:125], v[128:129]
	v_pk_mul_f32 v[126:127], v[126:127], v[130:131]
	v_pk_mul_f32 v[84:85], v[84:85], v[132:133]
	v_pk_mul_f32 v[86:87], v[86:87], v[134:135]
	v_pk_mul_f32 v[92:93], v[92:93], v[132:133]
	v_pk_mul_f32 v[94:95], v[94:95], v[134:135]
	v_pk_mul_f32 v[100:101], v[100:101], v[132:133]
	v_pk_mul_f32 v[102:103], v[102:103], v[134:135]
	ds_write2_b64 v69, v[108:109], v[64:65] offset0:192 offset1:196
	v_pk_mul_f32 v[64:65], v[72:73], v[132:133]
	v_pk_mul_f32 v[66:67], v[74:75], v[134:135]
	v_pk_mul_f32 v[46:47], v[60:61], v[136:137]
	v_pk_mul_f32 v[48:49], v[62:63], v[138:139]
	ds_write2_b64 v69, v[44:45], v[0:1] offset0:200 offset1:204
	v_pk_mul_f32 v[0:1], v[28:29], v[140:141]
	v_pk_mul_f32 v[2:3], v[30:31], v[142:143]
	v_cvt_pk_bf16_f32 v96, v104, v105
	v_cvt_pk_bf16_f32 v99, v110, v111
	v_cvt_pk_bf16_f32 v104, v112, v113
	v_cvt_pk_bf16_f32 v105, v114, v115
	v_cvt_pk_bf16_f32 v110, v124, v125
	v_cvt_pk_bf16_f32 v111, v126, v127
	v_cvt_pk_bf16_f32 v76, v84, v85
	v_cvt_pk_bf16_f32 v77, v86, v87
	v_cvt_pk_bf16_f32 v78, v92, v93
	v_cvt_pk_bf16_f32 v79, v94, v95
	v_cvt_pk_bf16_f32 v84, v100, v101
	v_cvt_pk_bf16_f32 v85, v102, v103
	v_cvt_pk_bf16_f32 v64, v64, v65
	v_cvt_pk_bf16_f32 v65, v66, v67
	v_add_u32_e32 v66, 0x7000, v144
	v_cvt_pk_bf16_f32 v46, v46, v47
	v_cvt_pk_bf16_f32 v47, v48, v49
	v_cvt_pk_bf16_f32 v0, v0, v1
	v_cvt_pk_bf16_f32 v1, v2, v3
	v_mov_b32_e32 v2, v218
	ds_write2_b64 v146, v[96:97], v[76:77] offset0:64 offset1:68
	ds_write2_b64 v147, v[98:99], v[78:79] offset0:96 offset1:100
	ds_write2_b64 v148, v[104:105], v[84:85] offset0:128 offset1:132
	ds_write2_b64 v66, v[110:111], v[64:65] offset0:224 offset1:228
	ds_write2_b64 v66, v[46:47], v[0:1] offset0:232 offset1:236
	s_waitcnt lgkmcnt(0)
	s_barrier
; DI int tidx() { int t = __builtin_amdgcn_workitem_id_x(); asm volatile("" : "+v"(t)); return t; }
; DI unsigned cvtpk(float lo, float hi) { const f32x2_ v = {lo, hi}; return __builtin_bit_cast(unsigned, __builtin_convertvector(v, bf16x2_)); }
; DI float bflo(unsigned w) { return __uint_as_float(w << 16); }
; DI float bfhi(unsigned w) { return __uint_as_float(w & 0xffff0000u); }
; DI void phase6(const Params& p, const Sched& sched, unsigned char* smem) {
;     ...
;       const int tid = tidx();
; #pragma unroll
;       for (int i = 0; i < 16; ++i) {
;         const int c = tid + 256 * i, row = c >> 4, ch = (c & 15) * 8;
;         const size_t gi = (size_t)(tm * 256 + row) * 1024 + tn * 128 + ch;
;         const u32x4 sv = *(const u32x4*)(Ls + row * EST + ch);
;         const f32x4 x0 = *(const f32x4*)(p.x + gi), x1 = *(const f32x4*)(p.x + gi + 4);
;         u32x4 w;
;         w.x = cvtpk(x0[0] + bflo(sv.x), x0[1] + bfhi(sv.x)); w.y = cvtpk(x0[2] + bflo(sv.y), x0[3] + bfhi(sv.y));
;         w.z = cvtpk(x1[0] + bflo(sv.z), x1[1] + bfhi(sv.z)); w.w = cvtpk(x1[2] + bflo(sv.w), x1[3] + bfhi(sv.w));
;         *(u32x4*)(x1b + gi) = w;
;       }
	v_ashrrev_i32_e32 v204, 4, v218
	v_lshlrev_b32_e32 v205, 3, v218
	v_and_b32_e32 v205, 0x78, v205
	v_add_u32_e32 v206, s33, v204
	v_ashrrev_i32_e32 v207, 31, v206
	v_lshlrev_b64 v[206:207], 10, v[206:207]
	v_or3_b32 v206, v206, s34, v205
	v_lshl_add_u64 v[200:201], v[206:207], 2, s[76:77]
	v_lshl_add_u64 v[202:203], v[206:207], 1, s[12:13]
	v_mul_u32_u24_e32 v204, 0x110, v204
	v_lshl_add_u32 v204, v205, 1, v204
	s_mov_b64 s[98:99], 0x10000
	s_mov_b64 s[100:101], 0x8000
	global_load_dwordx4 v[0:3], v[200:201], off
	global_load_dwordx4 v[4:7], v[200:201], off offset:16
	v_lshl_add_u64 v[200:201], v[200:201], 0, s[98:99]
	global_load_dwordx4 v[8:11], v[200:201], off
	global_load_dwordx4 v[12:15], v[200:201], off offset:16
	v_lshl_add_u64 v[200:201], v[200:201], 0, s[98:99]
	global_load_dwordx4 v[16:19], v[200:201], off
	global_load_dwordx4 v[20:23], v[200:201], off offset:16
	v_lshl_add_u64 v[200:201], v[200:201], 0, s[98:99]
	global_load_dwordx4 v[24:27], v[200:201], off
	global_load_dwordx4 v[28:31], v[200:201], off offset:16
	v_lshl_add_u64 v[200:201], v[200:201], 0, s[98:99]
	global_load_dwordx4 v[32:35], v[200:201], off
	global_load_dwordx4 v[36:39], v[200:201], off offset:16
	v_lshl_add_u64 v[200:201], v[200:201], 0, s[98:99]
	global_load_dwordx4 v[40:43], v[200:201], off
	global_load_dwordx4 v[44:47], v[200:201], off offset:16
	v_lshl_add_u64 v[200:201], v[200:201], 0, s[98:99]
	global_load_dwordx4 v[48:51], v[200:201], off
	global_load_dwordx4 v[52:55], v[200:201], off offset:16
	v_lshl_add_u64 v[200:201], v[200:201], 0, s[98:99]
	global_load_dwordx4 v[56:59], v[200:201], off
	global_load_dwordx4 v[60:63], v[200:201], off offset:16
	v_lshl_add_u64 v[200:201], v[200:201], 0, s[98:99]
	global_load_dwordx4 v[64:67], v[200:201], off
	global_load_dwordx4 v[68:71], v[200:201], off offset:16
	v_lshl_add_u64 v[200:201], v[200:201], 0, s[98:99]
	global_load_dwordx4 v[72:75], v[200:201], off
	global_load_dwordx4 v[76:79], v[200:201], off offset:16
	v_lshl_add_u64 v[200:201], v[200:201], 0, s[98:99]
	global_load_dwordx4 v[80:83], v[200:201], off
	global_load_dwordx4 v[84:87], v[200:201], off offset:16
	v_lshl_add_u64 v[200:201], v[200:201], 0, s[98:99]
	global_load_dwordx4 v[88:91], v[200:201], off
	global_load_dwordx4 v[92:95], v[200:201], off offset:16
	v_lshl_add_u64 v[200:201], v[200:201], 0, s[98:99]
	global_load_dwordx4 v[96:99], v[200:201], off
	global_load_dwordx4 v[100:103], v[200:201], off offset:16
	v_lshl_add_u64 v[200:201], v[200:201], 0, s[98:99]
	global_load_dwordx4 v[104:107], v[200:201], off
	global_load_dwordx4 v[108:111], v[200:201], off offset:16
	v_lshl_add_u64 v[200:201], v[200:201], 0, s[98:99]
	global_load_dwordx4 v[112:115], v[200:201], off
	global_load_dwordx4 v[116:119], v[200:201], off offset:16
	v_lshl_add_u64 v[200:201], v[200:201], 0, s[98:99]
	global_load_dwordx4 v[120:123], v[200:201], off
	global_load_dwordx4 v[124:127], v[200:201], off offset:16
	ds_read_b128 v[128:131], v204 offset:0
	ds_read_b128 v[132:135], v204 offset:4352
	ds_read_b128 v[136:139], v204 offset:8704
	ds_read_b128 v[140:143], v204 offset:13056
	s_waitcnt lgkmcnt(3)
	v_lshlrev_b32_e32 v208, 16, v128
	v_and_b32_e32 v209, 0xffff0000, v128
	v_lshlrev_b32_e32 v210, 16, v129
	v_and_b32_e32 v211, 0xffff0000, v129
	v_lshlrev_b32_e32 v212, 16, v130
	v_and_b32_e32 v213, 0xffff0000, v130
	v_lshlrev_b32_e32 v214, 16, v131
	v_and_b32_e32 v215, 0xffff0000, v131
	ds_read_b128 v[128:131], v204 offset:17408
	s_waitcnt vmcnt(31)
	v_pk_add_f32 v[0:1], v[0:1], v[208:209]
	v_pk_add_f32 v[2:3], v[2:3], v[210:211]
	s_waitcnt vmcnt(30)
	v_pk_add_f32 v[4:5], v[4:5], v[212:213]
	v_pk_add_f32 v[6:7], v[6:7], v[214:215]
	v_cvt_pk_bf16_f32 v0, v0, v1
	v_cvt_pk_bf16_f32 v1, v2, v3
	v_cvt_pk_bf16_f32 v2, v4, v5
	v_cvt_pk_bf16_f32 v3, v6, v7
	global_store_dwordx4 v[202:203], v[0:3], off
	v_lshl_add_u64 v[202:203], v[202:203], 0, s[100:101]
	s_waitcnt lgkmcnt(3)
	v_lshlrev_b32_e32 v208, 16, v132
	v_and_b32_e32 v209, 0xffff0000, v132
	v_lshlrev_b32_e32 v210, 16, v133
	v_and_b32_e32 v211, 0xffff0000, v133
	v_lshlrev_b32_e32 v212, 16, v134
	v_and_b32_e32 v213, 0xffff0000, v134
	v_lshlrev_b32_e32 v214, 16, v135
	v_and_b32_e32 v215, 0xffff0000, v135
	ds_read_b128 v[132:135], v204 offset:21760
	s_waitcnt vmcnt(29)
	v_pk_add_f32 v[8:9], v[8:9], v[208:209]
	v_pk_add_f32 v[10:11], v[10:11], v[210:211]
	s_waitcnt vmcnt(28)
	v_pk_add_f32 v[12:13], v[12:13], v[212:213]
	v_pk_add_f32 v[14:15], v[14:15], v[214:215]
	v_cvt_pk_bf16_f32 v8, v8, v9
	v_cvt_pk_bf16_f32 v9, v10, v11
	v_cvt_pk_bf16_f32 v10, v12, v13
	v_cvt_pk_bf16_f32 v11, v14, v15
	global_store_dwordx4 v[202:203], v[8:11], off
	v_lshl_add_u64 v[202:203], v[202:203], 0, s[100:101]
	s_waitcnt lgkmcnt(3)
	v_lshlrev_b32_e32 v208, 16, v136
	v_and_b32_e32 v209, 0xffff0000, v136
	v_lshlrev_b32_e32 v210, 16, v137
	v_and_b32_e32 v211, 0xffff0000, v137
	v_lshlrev_b32_e32 v212, 16, v138
	v_and_b32_e32 v213, 0xffff0000, v138
	v_lshlrev_b32_e32 v214, 16, v139
	v_and_b32_e32 v215, 0xffff0000, v139
	ds_read_b128 v[136:139], v204 offset:26112
	s_waitcnt vmcnt(27)
	v_pk_add_f32 v[16:17], v[16:17], v[208:209]
	v_pk_add_f32 v[18:19], v[18:19], v[210:211]
	s_waitcnt vmcnt(26)
	v_pk_add_f32 v[20:21], v[20:21], v[212:213]
	v_pk_add_f32 v[22:23], v[22:23], v[214:215]
	v_cvt_pk_bf16_f32 v16, v16, v17
	v_cvt_pk_bf16_f32 v17, v18, v19
	v_cvt_pk_bf16_f32 v18, v20, v21
	v_cvt_pk_bf16_f32 v19, v22, v23
	global_store_dwordx4 v[202:203], v[16:19], off
	v_lshl_add_u64 v[202:203], v[202:203], 0, s[100:101]
	s_waitcnt lgkmcnt(3)
; DI int tidx() { int t = __builtin_amdgcn_workitem_id_x(); asm volatile("" : "+v"(t)); return t; }
; DI unsigned cvtpk(float lo, float hi) { const f32x2_ v = {lo, hi}; return __builtin_bit_cast(unsigned, __builtin_convertvector(v, bf16x2_)); }
; DI float bflo(unsigned w) { return __uint_as_float(w << 16); }
; DI float bfhi(unsigned w) { return __uint_as_float(w & 0xffff0000u); }
; DI void phase6(const Params& p, const Sched& sched, unsigned char* smem) {
;     ...
;       const int tid = tidx();
; #pragma unroll
;       for (int i = 0; i < 16; ++i) {
;         const int c = tid + 256 * i, row = c >> 4, ch = (c & 15) * 8;
;         const size_t gi = (size_t)(tm * 256 + row) * 1024 + tn * 128 + ch;
;         const u32x4 sv = *(const u32x4*)(Ls + row * EST + ch);
;         const f32x4 x0 = *(const f32x4*)(p.x + gi), x1 = *(const f32x4*)(p.x + gi + 4);
;         u32x4 w;
;         w.x = cvtpk(x0[0] + bflo(sv.x), x0[1] + bfhi(sv.x)); w.y = cvtpk(x0[2] + bflo(sv.y), x0[3] + bfhi(sv.y));
;         w.z = cvtpk(x1[0] + bflo(sv.z), x1[1] + bfhi(sv.z)); w.w = cvtpk(x1[2] + bflo(sv.w), x1[3] + bfhi(sv.w));
;         *(u32x4*)(x1b + gi) = w;
;       }
	v_lshlrev_b32_e32 v208, 16, v140
	v_and_b32_e32 v209, 0xffff0000, v140
	v_lshlrev_b32_e32 v210, 16, v141
	v_and_b32_e32 v211, 0xffff0000, v141
	v_lshlrev_b32_e32 v212, 16, v142
	v_and_b32_e32 v213, 0xffff0000, v142
	v_lshlrev_b32_e32 v214, 16, v143
	v_and_b32_e32 v215, 0xffff0000, v143
	ds_read_b128 v[140:143], v204 offset:30464
	s_waitcnt vmcnt(25)
	v_pk_add_f32 v[24:25], v[24:25], v[208:209]
	v_pk_add_f32 v[26:27], v[26:27], v[210:211]
	s_waitcnt vmcnt(24)
	v_pk_add_f32 v[28:29], v[28:29], v[212:213]
	v_pk_add_f32 v[30:31], v[30:31], v[214:215]
	v_cvt_pk_bf16_f32 v24, v24, v25
	v_cvt_pk_bf16_f32 v25, v26, v27
	v_cvt_pk_bf16_f32 v26, v28, v29
	v_cvt_pk_bf16_f32 v27, v30, v31
	global_store_dwordx4 v[202:203], v[24:27], off
	v_lshl_add_u64 v[202:203], v[202:203], 0, s[100:101]
	s_waitcnt lgkmcnt(3)
	v_lshlrev_b32_e32 v208, 16, v128
	v_and_b32_e32 v209, 0xffff0000, v128
	v_lshlrev_b32_e32 v210, 16, v129
	v_and_b32_e32 v211, 0xffff0000, v129
	v_lshlrev_b32_e32 v212, 16, v130
	v_and_b32_e32 v213, 0xffff0000, v130
	v_lshlrev_b32_e32 v214, 16, v131
	v_and_b32_e32 v215, 0xffff0000, v131
	ds_read_b128 v[128:131], v204 offset:34816
	s_waitcnt vmcnt(23)
	v_pk_add_f32 v[32:33], v[32:33], v[208:209]
	v_pk_add_f32 v[34:35], v[34:35], v[210:211]
	s_waitcnt vmcnt(22)
	v_pk_add_f32 v[36:37], v[36:37], v[212:213]
	v_pk_add_f32 v[38:39], v[38:39], v[214:215]
	v_cvt_pk_bf16_f32 v32, v32, v33
	v_cvt_pk_bf16_f32 v33, v34, v35
	v_cvt_pk_bf16_f32 v34, v36, v37
	v_cvt_pk_bf16_f32 v35, v38, v39
	global_store_dwordx4 v[202:203], v[32:35], off
	v_lshl_add_u64 v[202:203], v[202:203], 0, s[100:101]
	s_waitcnt lgkmcnt(3)
	v_lshlrev_b32_e32 v208, 16, v132
	v_and_b32_e32 v209, 0xffff0000, v132
	v_lshlrev_b32_e32 v210, 16, v133
	v_and_b32_e32 v211, 0xffff0000, v133
	v_lshlrev_b32_e32 v212, 16, v134
	v_and_b32_e32 v213, 0xffff0000, v134
	v_lshlrev_b32_e32 v214, 16, v135
	v_and_b32_e32 v215, 0xffff0000, v135
	ds_read_b128 v[132:135], v204 offset:39168
	s_waitcnt vmcnt(21)
	v_pk_add_f32 v[40:41], v[40:41], v[208:209]
	v_pk_add_f32 v[42:43], v[42:43], v[210:211]
	s_waitcnt vmcnt(20)
	v_pk_add_f32 v[44:45], v[44:45], v[212:213]
	v_pk_add_f32 v[46:47], v[46:47], v[214:215]
	v_cvt_pk_bf16_f32 v40, v40, v41
	v_cvt_pk_bf16_f32 v41, v42, v43
	v_cvt_pk_bf16_f32 v42, v44, v45
	v_cvt_pk_bf16_f32 v43, v46, v47
	global_store_dwordx4 v[202:203], v[40:43], off
	v_lshl_add_u64 v[202:203], v[202:203], 0, s[100:101]
	s_waitcnt lgkmcnt(3)
	v_lshlrev_b32_e32 v208, 16, v136
	v_and_b32_e32 v209, 0xffff0000, v136
	v_lshlrev_b32_e32 v210, 16, v137
	v_and_b32_e32 v211, 0xffff0000, v137
	v_lshlrev_b32_e32 v212, 16, v138
	v_and_b32_e32 v213, 0xffff0000, v138
	v_lshlrev_b32_e32 v214, 16, v139
	v_and_b32_e32 v215, 0xffff0000, v139
	ds_read_b128 v[136:139], v204 offset:43520
	s_waitcnt vmcnt(19)
	v_pk_add_f32 v[48:49], v[48:49], v[208:209]
	v_pk_add_f32 v[50:51], v[50:51], v[210:211]
	s_waitcnt vmcnt(18)
	v_pk_add_f32 v[52:53], v[52:53], v[212:213]
	v_pk_add_f32 v[54:55], v[54:55], v[214:215]
	v_cvt_pk_bf16_f32 v48, v48, v49
	v_cvt_pk_bf16_f32 v49, v50, v51
	v_cvt_pk_bf16_f32 v50, v52, v53
	v_cvt_pk_bf16_f32 v51, v54, v55
	global_store_dwordx4 v[202:203], v[48:51], off
	v_lshl_add_u64 v[202:203], v[202:203], 0, s[100:101]
	s_waitcnt lgkmcnt(3)
	v_lshlrev_b32_e32 v208, 16, v140
	v_and_b32_e32 v209, 0xffff0000, v140
	v_lshlrev_b32_e32 v210, 16, v141
	v_and_b32_e32 v211, 0xffff0000, v141
	v_lshlrev_b32_e32 v212, 16, v142
	v_and_b32_e32 v213, 0xffff0000, v142
	v_lshlrev_b32_e32 v214, 16, v143
	v_and_b32_e32 v215, 0xffff0000, v143
	ds_read_b128 v[140:143], v204 offset:47872
	s_waitcnt vmcnt(17)
	v_pk_add_f32 v[56:57], v[56:57], v[208:209]
	v_pk_add_f32 v[58:59], v[58:59], v[210:211]
	s_waitcnt vmcnt(16)
	v_pk_add_f32 v[60:61], v[60:61], v[212:213]
	v_pk_add_f32 v[62:63], v[62:63], v[214:215]
	v_cvt_pk_bf16_f32 v56, v56, v57
	v_cvt_pk_bf16_f32 v57, v58, v59
	v_cvt_pk_bf16_f32 v58, v60, v61
	v_cvt_pk_bf16_f32 v59, v62, v63
	global_store_dwordx4 v[202:203], v[56:59], off
	v_lshl_add_u64 v[202:203], v[202:203], 0, s[100:101]
	s_waitcnt lgkmcnt(3)
	v_lshlrev_b32_e32 v208, 16, v128
	v_and_b32_e32 v209, 0xffff0000, v128
	v_lshlrev_b32_e32 v210, 16, v129
	v_and_b32_e32 v211, 0xffff0000, v129
	v_lshlrev_b32_e32 v212, 16, v130
	v_and_b32_e32 v213, 0xffff0000, v130
	v_lshlrev_b32_e32 v214, 16, v131
	v_and_b32_e32 v215, 0xffff0000, v131
	ds_read_b128 v[128:131], v204 offset:52224
	s_waitcnt vmcnt(15)
	v_pk_add_f32 v[64:65], v[64:65], v[208:209]
	v_pk_add_f32 v[66:67], v[66:67], v[210:211]
	s_waitcnt vmcnt(14)
	v_pk_add_f32 v[68:69], v[68:69], v[212:213]
	v_pk_add_f32 v[70:71], v[70:71], v[214:215]
	v_cvt_pk_bf16_f32 v64, v64, v65
	v_cvt_pk_bf16_f32 v65, v66, v67
	v_cvt_pk_bf16_f32 v66, v68, v69
	v_cvt_pk_bf16_f32 v67, v70, v71
	global_store_dwordx4 v[202:203], v[64:67], off
	v_lshl_add_u64 v[202:203], v[202:203], 0, s[100:101]
	s_waitcnt lgkmcnt(3)
	v_lshlrev_b32_e32 v208, 16, v132
	v_and_b32_e32 v209, 0xffff0000, v132
	v_lshlrev_b32_e32 v210, 16, v133
	v_and_b32_e32 v211, 0xffff0000, v133
	v_lshlrev_b32_e32 v212, 16, v134
	v_and_b32_e32 v213, 0xffff0000, v134
	v_lshlrev_b32_e32 v214, 16, v135
	v_and_b32_e32 v215, 0xffff0000, v135
	ds_read_b128 v[132:135], v204 offset:56576
	s_waitcnt vmcnt(13)
; DI int tidx() { int t = __builtin_amdgcn_workitem_id_x(); asm volatile("" : "+v"(t)); return t; }
; DI unsigned cvtpk(float lo, float hi) { const f32x2_ v = {lo, hi}; return __builtin_bit_cast(unsigned, __builtin_convertvector(v, bf16x2_)); }
; DI float bflo(unsigned w) { return __uint_as_float(w << 16); }
; DI float bfhi(unsigned w) { return __uint_as_float(w & 0xffff0000u); }
; DI void phase6(const Params& p, const Sched& sched, unsigned char* smem) {
;     ...
;       const int tid = tidx();
; #pragma unroll
;       for (int i = 0; i < 16; ++i) {
;         const int c = tid + 256 * i, row = c >> 4, ch = (c & 15) * 8;
;         const size_t gi = (size_t)(tm * 256 + row) * 1024 + tn * 128 + ch;
;         const u32x4 sv = *(const u32x4*)(Ls + row * EST + ch);
;         const f32x4 x0 = *(const f32x4*)(p.x + gi), x1 = *(const f32x4*)(p.x + gi + 4);
;         u32x4 w;
;         w.x = cvtpk(x0[0] + bflo(sv.x), x0[1] + bfhi(sv.x)); w.y = cvtpk(x0[2] + bflo(sv.y), x0[3] + bfhi(sv.y));
;         w.z = cvtpk(x1[0] + bflo(sv.z), x1[1] + bfhi(sv.z)); w.w = cvtpk(x1[2] + bflo(sv.w), x1[3] + bfhi(sv.w));
;         *(u32x4*)(x1b + gi) = w;
;       }
	v_pk_add_f32 v[72:73], v[72:73], v[208:209]
	v_pk_add_f32 v[74:75], v[74:75], v[210:211]
	s_waitcnt vmcnt(12)
	v_pk_add_f32 v[76:77], v[76:77], v[212:213]
	v_pk_add_f32 v[78:79], v[78:79], v[214:215]
	v_cvt_pk_bf16_f32 v72, v72, v73
	v_cvt_pk_bf16_f32 v73, v74, v75
	v_cvt_pk_bf16_f32 v74, v76, v77
	v_cvt_pk_bf16_f32 v75, v78, v79
	global_store_dwordx4 v[202:203], v[72:75], off
	v_lshl_add_u64 v[202:203], v[202:203], 0, s[100:101]
	s_waitcnt lgkmcnt(3)
	v_lshlrev_b32_e32 v208, 16, v136
	v_and_b32_e32 v209, 0xffff0000, v136
	v_lshlrev_b32_e32 v210, 16, v137
	v_and_b32_e32 v211, 0xffff0000, v137
	v_lshlrev_b32_e32 v212, 16, v138
	v_and_b32_e32 v213, 0xffff0000, v138
	v_lshlrev_b32_e32 v214, 16, v139
	v_and_b32_e32 v215, 0xffff0000, v139
	ds_read_b128 v[136:139], v204 offset:60928
	s_waitcnt vmcnt(11)
	v_pk_add_f32 v[80:81], v[80:81], v[208:209]
	v_pk_add_f32 v[82:83], v[82:83], v[210:211]
	s_waitcnt vmcnt(10)
	v_pk_add_f32 v[84:85], v[84:85], v[212:213]
	v_pk_add_f32 v[86:87], v[86:87], v[214:215]
	v_cvt_pk_bf16_f32 v80, v80, v81
	v_cvt_pk_bf16_f32 v81, v82, v83
	v_cvt_pk_bf16_f32 v82, v84, v85
	v_cvt_pk_bf16_f32 v83, v86, v87
	global_store_dwordx4 v[202:203], v[80:83], off
	v_lshl_add_u64 v[202:203], v[202:203], 0, s[100:101]
	s_waitcnt lgkmcnt(3)
	v_lshlrev_b32_e32 v208, 16, v140
	v_and_b32_e32 v209, 0xffff0000, v140
	v_lshlrev_b32_e32 v210, 16, v141
	v_and_b32_e32 v211, 0xffff0000, v141
	v_lshlrev_b32_e32 v212, 16, v142
	v_and_b32_e32 v213, 0xffff0000, v142
	v_lshlrev_b32_e32 v214, 16, v143
	v_and_b32_e32 v215, 0xffff0000, v143
	ds_read_b128 v[140:143], v204 offset:65280
	s_waitcnt vmcnt(9)
	v_pk_add_f32 v[88:89], v[88:89], v[208:209]
	v_pk_add_f32 v[90:91], v[90:91], v[210:211]
	s_waitcnt vmcnt(8)
	v_pk_add_f32 v[92:93], v[92:93], v[212:213]
	v_pk_add_f32 v[94:95], v[94:95], v[214:215]
	v_cvt_pk_bf16_f32 v88, v88, v89
	v_cvt_pk_bf16_f32 v89, v90, v91
	v_cvt_pk_bf16_f32 v90, v92, v93
	v_cvt_pk_bf16_f32 v91, v94, v95
	global_store_dwordx4 v[202:203], v[88:91], off
	v_lshl_add_u64 v[202:203], v[202:203], 0, s[100:101]
	s_waitcnt lgkmcnt(3)
	v_lshlrev_b32_e32 v208, 16, v128
	v_and_b32_e32 v209, 0xffff0000, v128
	v_lshlrev_b32_e32 v210, 16, v129
	v_and_b32_e32 v211, 0xffff0000, v129
	v_lshlrev_b32_e32 v212, 16, v130
	v_and_b32_e32 v213, 0xffff0000, v130
	v_lshlrev_b32_e32 v214, 16, v131
	v_and_b32_e32 v215, 0xffff0000, v131
	s_waitcnt vmcnt(7)
	v_pk_add_f32 v[96:97], v[96:97], v[208:209]
	v_pk_add_f32 v[98:99], v[98:99], v[210:211]
	s_waitcnt vmcnt(6)
	v_pk_add_f32 v[100:101], v[100:101], v[212:213]
	v_pk_add_f32 v[102:103], v[102:103], v[214:215]
	v_cvt_pk_bf16_f32 v96, v96, v97
	v_cvt_pk_bf16_f32 v97, v98, v99
	v_cvt_pk_bf16_f32 v98, v100, v101
	v_cvt_pk_bf16_f32 v99, v102, v103
	global_store_dwordx4 v[202:203], v[96:99], off
	v_lshl_add_u64 v[202:203], v[202:203], 0, s[100:101]
	s_waitcnt lgkmcnt(2)
	v_lshlrev_b32_e32 v208, 16, v132
	v_and_b32_e32 v209, 0xffff0000, v132
	v_lshlrev_b32_e32 v210, 16, v133
	v_and_b32_e32 v211, 0xffff0000, v133
	v_lshlrev_b32_e32 v212, 16, v134
	v_and_b32_e32 v213, 0xffff0000, v134
	v_lshlrev_b32_e32 v214, 16, v135
	v_and_b32_e32 v215, 0xffff0000, v135
	s_waitcnt vmcnt(5)
	v_pk_add_f32 v[104:105], v[104:105], v[208:209]
	v_pk_add_f32 v[106:107], v[106:107], v[210:211]
	s_waitcnt vmcnt(4)
	v_pk_add_f32 v[108:109], v[108:109], v[212:213]
	v_pk_add_f32 v[110:111], v[110:111], v[214:215]
	v_cvt_pk_bf16_f32 v104, v104, v105
	v_cvt_pk_bf16_f32 v105, v106, v107
	v_cvt_pk_bf16_f32 v106, v108, v109
	v_cvt_pk_bf16_f32 v107, v110, v111
	global_store_dwordx4 v[202:203], v[104:107], off
	v_lshl_add_u64 v[202:203], v[202:203], 0, s[100:101]
	s_waitcnt lgkmcnt(1)
	v_lshlrev_b32_e32 v208, 16, v136
	v_and_b32_e32 v209, 0xffff0000, v136
	v_lshlrev_b32_e32 v210, 16, v137
	v_and_b32_e32 v211, 0xffff0000, v137
	v_lshlrev_b32_e32 v212, 16, v138
	v_and_b32_e32 v213, 0xffff0000, v138
	v_lshlrev_b32_e32 v214, 16, v139
	v_and_b32_e32 v215, 0xffff0000, v139
	s_waitcnt vmcnt(3)
	v_pk_add_f32 v[112:113], v[112:113], v[208:209]
	v_pk_add_f32 v[114:115], v[114:115], v[210:211]
	s_waitcnt vmcnt(2)
	v_pk_add_f32 v[116:117], v[116:117], v[212:213]
	v_pk_add_f32 v[118:119], v[118:119], v[214:215]
	v_cvt_pk_bf16_f32 v112, v112, v113
	v_cvt_pk_bf16_f32 v113, v114, v115
	v_cvt_pk_bf16_f32 v114, v116, v117
	v_cvt_pk_bf16_f32 v115, v118, v119
	global_store_dwordx4 v[202:203], v[112:115], off
	v_lshl_add_u64 v[202:203], v[202:203], 0, s[100:101]
	s_waitcnt lgkmcnt(0)
	v_lshlrev_b32_e32 v208, 16, v140
	v_and_b32_e32 v209, 0xffff0000, v140
	v_lshlrev_b32_e32 v210, 16, v141
	v_and_b32_e32 v211, 0xffff0000, v141
	v_lshlrev_b32_e32 v212, 16, v142
	v_and_b32_e32 v213, 0xffff0000, v142
	v_lshlrev_b32_e32 v214, 16, v143
	v_and_b32_e32 v215, 0xffff0000, v143
	s_waitcnt vmcnt(1)
	v_pk_add_f32 v[120:121], v[120:121], v[208:209]
	v_pk_add_f32 v[122:123], v[122:123], v[210:211]
	s_waitcnt vmcnt(0)
	v_pk_add_f32 v[124:125], v[124:125], v[212:213]
	v_pk_add_f32 v[126:127], v[126:127], v[214:215]
	v_cvt_pk_bf16_f32 v120, v120, v121
	v_cvt_pk_bf16_f32 v121, v122, v123
	v_cvt_pk_bf16_f32 v122, v124, v125
	v_cvt_pk_bf16_f32 v123, v126, v127
	global_store_dwordx4 v[202:203], v[120:123], off
	s_cbranch_scc0 .LBB0_811
	s_branch .LBB0_808

; DI f32x4 mfma16(bf16x8 a, bf16x8 b, f32x4 c) { return __builtin_amdgcn_mfma_f32_16x16x32_bf16(a, b, c, 0, 0, 0); }
; template <int NI, class XL, class EP>
; DI void gemm_tile(const u16* __restrict__ W, int ldw, int f0, int t0, int K, XL xl, EP ep, unsigned char* smem) {
;     ...
;   for (int it = 0; it < nk; ++it) {
;     const u16* Ws = S0 + (it & 1) * BUF; const u16* Xs = Ws + 128 * LST;
;     __builtin_amdgcn_s_setprio(1);
;     bf16x8 a[4];
; #pragma unroll
;     for (int mi = 0; mi < 4; ++mi) a[mi] = *(const bf16x8*)(Ws + (wf * 64 + mi * 16 + lr) * LST + lq * 8);
; #pragma unroll
;     for (int ni = 0; ni < NI; ++ni) {
;       const bf16x8 b = *(const bf16x8*)(Xs + (wt * (NI * 16) + ni * 16 + lr) * LST + lq * 8);
; #pragma unroll
;       for (int mi = 0; mi < 4; ++mi) acc[mi][ni] = mfma16(a[mi], b, acc[mi][ni]);
;     }
;     __builtin_amdgcn_sched_group_barrier(0x100, 6, 0);
; #pragma unroll
;     for (int ni = 0; ni < NI; ++ni) { __builtin_amdgcn_sched_group_barrier(0x008, 4, 0); if (ni + 2 < NI) __builtin_amdgcn_sched_group_barrier(0x100, 1, 0); }
;     __builtin_amdgcn_s_setprio(0);
;     if (it + 1 < nk) lstore((it + 1) & 1);
;     if (it + 2 < nk) gload(it + 2);
;     __syncthreads();
;   }
.LBB0_1095:
	s_setprio 1
	ds_read_b128 v[168:171], v228 offset:0
	ds_read_b128 v[172:175], v228 offset:1536
	ds_read_b128 v[180:183], v228 offset:3072
	ds_read_b128 v[184:187], v228 offset:4608
	ds_read_b128 v[176:179], v152 offset:12288
	ds_read_b128 v[188:191], v152 offset:13824
	s_waitcnt lgkmcnt(1)
	v_mfma_f32_16x16x32_bf16 v[148:151], v[168:171], v[176:179], v[148:151]
	v_mfma_f32_16x16x32_bf16 v[136:139], v[172:175], v[176:179], v[136:139]
	v_mfma_f32_16x16x32_bf16 v[112:115], v[180:183], v[176:179], v[112:115]
	v_mfma_f32_16x16x32_bf16 v[80:83], v[184:187], v[176:179], v[80:83]
	ds_read_b128 v[176:179], v152 offset:15360
	s_waitcnt vmcnt(6)
	ds_write_b128 v229, v[20:23] offset:36864
	s_waitcnt lgkmcnt(2)
	v_mfma_f32_16x16x32_bf16 v[144:147], v[168:171], v[188:191], v[144:147]
	v_mfma_f32_16x16x32_bf16 v[128:131], v[172:175], v[188:191], v[128:131]
	v_mfma_f32_16x16x32_bf16 v[100:103], v[180:183], v[188:191], v[100:103]
	v_mfma_f32_16x16x32_bf16 v[68:71], v[184:187], v[188:191], v[68:71]
	ds_read_b128 v[188:191], v152 offset:16896
	ds_write_b128 v229, v[16:19] offset:36960
	global_load_dwordx4 v[20:23], v154, s[98:99]
	global_load_dwordx4 v[16:19], v154, s[98:99] offset:64
	s_waitcnt lgkmcnt(3)
	v_mfma_f32_16x16x32_bf16 v[140:143], v[168:171], v[176:179], v[140:143]
	v_mfma_f32_16x16x32_bf16 v[120:123], v[172:175], v[176:179], v[120:123]
	v_mfma_f32_16x16x32_bf16 v[88:91], v[180:183], v[176:179], v[88:91]
	v_mfma_f32_16x16x32_bf16 v[44:47], v[184:187], v[176:179], v[44:47]
	ds_read_b128 v[176:179], v152 offset:18432
	ds_write_b128 v230, v[36:39] offset:49152
	global_load_dwordx4 v[36:39], v156, s[100:101] offset:2048
	s_waitcnt lgkmcnt(3)
	v_mfma_f32_16x16x32_bf16 v[132:135], v[168:171], v[188:191], v[132:135]
	v_mfma_f32_16x16x32_bf16 v[108:111], v[172:175], v[188:191], v[108:111]
	v_mfma_f32_16x16x32_bf16 v[76:79], v[180:183], v[188:191], v[76:79]
	v_mfma_f32_16x16x32_bf16 v[40:43], v[184:187], v[188:191], v[40:43]
	ds_read_b128 v[188:191], v152 offset:19968
	ds_write_b128 v230, v[32:35] offset:49248
	global_load_dwordx4 v[32:35], v156, s[100:101] offset:2112
	s_waitcnt lgkmcnt(3)
	v_mfma_f32_16x16x32_bf16 v[124:127], v[168:171], v[176:179], v[124:127]
	v_mfma_f32_16x16x32_bf16 v[96:99], v[172:175], v[176:179], v[96:99]
	v_mfma_f32_16x16x32_bf16 v[64:67], v[180:183], v[176:179], v[64:67]
	v_mfma_f32_16x16x32_bf16 v[12:15], v[184:187], v[176:179], v[12:15]
	ds_read_b128 v[176:179], v152 offset:21504
	ds_write_b128 v230, v[28:31] offset:49344
	global_load_dwordx4 v[28:31], v156, s[100:101] offset:2176
	s_waitcnt lgkmcnt(3)
	v_mfma_f32_16x16x32_bf16 v[116:119], v[168:171], v[188:191], v[116:119]
	v_mfma_f32_16x16x32_bf16 v[84:87], v[172:175], v[188:191], v[84:87]
	v_mfma_f32_16x16x32_bf16 v[56:59], v[180:183], v[188:191], v[56:59]
	v_mfma_f32_16x16x32_bf16 v[8:11], v[184:187], v[188:191], v[8:11]
	ds_read_b128 v[188:191], v152 offset:23040
	ds_write_b128 v230, v[24:27] offset:49440
	global_load_dwordx4 v[24:27], v156, s[100:101] offset:2240
	s_waitcnt lgkmcnt(3)
	v_mfma_f32_16x16x32_bf16 v[104:107], v[168:171], v[176:179], v[104:107]
	v_mfma_f32_16x16x32_bf16 v[72:75], v[172:175], v[176:179], v[72:75]
	v_mfma_f32_16x16x32_bf16 v[52:55], v[180:183], v[176:179], v[52:55]
	v_mfma_f32_16x16x32_bf16 v[4:7], v[184:187], v[176:179], v[4:7]
	s_add_u32 s98, s98, s16
	s_addc_u32 s99, s99, s17
	s_add_u32 s100, s100, s14
	s_addc_u32 s101, s101, s15
	s_waitcnt lgkmcnt(1)
	v_mfma_f32_16x16x32_bf16 v[92:95], v[168:171], v[188:191], v[92:95]
	v_mfma_f32_16x16x32_bf16 v[60:63], v[172:175], v[188:191], v[60:63]
	v_mfma_f32_16x16x32_bf16 v[48:51], v[180:183], v[188:191], v[48:51]
	v_mfma_f32_16x16x32_bf16 v[0:3], v[184:187], v[188:191], v[0:3]
	s_setprio 0
	s_waitcnt lgkmcnt(0)
	s_barrier
	s_setprio 1
	ds_read_b128 v[168:171], v228 offset:36864
	ds_read_b128 v[172:175], v228 offset:38400
	ds_read_b128 v[180:183], v228 offset:39936
	ds_read_b128 v[184:187], v228 offset:41472
	ds_read_b128 v[176:179], v152 offset:49152
	ds_read_b128 v[188:191], v152 offset:50688
	s_waitcnt lgkmcnt(1)
	v_mfma_f32_16x16x32_bf16 v[148:151], v[168:171], v[176:179], v[148:151]
	v_mfma_f32_16x16x32_bf16 v[136:139], v[172:175], v[176:179], v[136:139]
	v_mfma_f32_16x16x32_bf16 v[112:115], v[180:183], v[176:179], v[112:115]
	v_mfma_f32_16x16x32_bf16 v[80:83], v[184:187], v[176:179], v[80:83]
	ds_read_b128 v[176:179], v152 offset:52224
	s_waitcnt vmcnt(6)
	ds_write_b128 v229, v[200:203] offset:0
	s_waitcnt lgkmcnt(2)
	v_mfma_f32_16x16x32_bf16 v[144:147], v[168:171], v[188:191], v[144:147]
	v_mfma_f32_16x16x32_bf16 v[128:131], v[172:175], v[188:191], v[128:131]
	v_mfma_f32_16x16x32_bf16 v[100:103], v[180:183], v[188:191], v[100:103]
	v_mfma_f32_16x16x32_bf16 v[68:71], v[184:187], v[188:191], v[68:71]
	ds_read_b128 v[188:191], v152 offset:53760
	ds_write_b128 v229, v[204:207] offset:96
	global_load_dwordx4 v[200:203], v154, s[98:99]
	global_load_dwordx4 v[204:207], v154, s[98:99] offset:64
	s_waitcnt lgkmcnt(3)
	v_mfma_f32_16x16x32_bf16 v[140:143], v[168:171], v[176:179], v[140:143]
	v_mfma_f32_16x16x32_bf16 v[120:123], v[172:175], v[176:179], v[120:123]
	v_mfma_f32_16x16x32_bf16 v[88:91], v[180:183], v[176:179], v[88:91]
	v_mfma_f32_16x16x32_bf16 v[44:47], v[184:187], v[176:179], v[44:47]
	ds_read_b128 v[176:179], v152 offset:55296
	ds_write_b128 v230, v[208:211] offset:12288
	global_load_dwordx4 v[208:211], v156, s[100:101] offset:2048
	s_waitcnt lgkmcnt(3)
; DI f32x4 mfma16(bf16x8 a, bf16x8 b, f32x4 c) { return __builtin_amdgcn_mfma_f32_16x16x32_bf16(a, b, c, 0, 0, 0); }
; template <int NI, class XL, class EP>
; DI void gemm_tile(const u16* __restrict__ W, int ldw, int f0, int t0, int K, XL xl, EP ep, unsigned char* smem) {
;     ...
;   for (int it = 0; it < nk; ++it) {
;     const u16* Ws = S0 + (it & 1) * BUF; const u16* Xs = Ws + 128 * LST;
;     __builtin_amdgcn_s_setprio(1);
;     bf16x8 a[4];
; #pragma unroll
;     for (int mi = 0; mi < 4; ++mi) a[mi] = *(const bf16x8*)(Ws + (wf * 64 + mi * 16 + lr) * LST + lq * 8);
; #pragma unroll
;     for (int ni = 0; ni < NI; ++ni) {
;       const bf16x8 b = *(const bf16x8*)(Xs + (wt * (NI * 16) + ni * 16 + lr) * LST + lq * 8);
; #pragma unroll
;       for (int mi = 0; mi < 4; ++mi) acc[mi][ni] = mfma16(a[mi], b, acc[mi][ni]);
;     }
;     __builtin_amdgcn_sched_group_barrier(0x100, 6, 0);
; #pragma unroll
;     for (int ni = 0; ni < NI; ++ni) { __builtin_amdgcn_sched_group_barrier(0x008, 4, 0); if (ni + 2 < NI) __builtin_amdgcn_sched_group_barrier(0x100, 1, 0); }
;     __builtin_amdgcn_s_setprio(0);
;     if (it + 1 < nk) lstore((it + 1) & 1);
;     if (it + 2 < nk) gload(it + 2);
;     __syncthreads();
;   }
	v_mfma_f32_16x16x32_bf16 v[132:135], v[168:171], v[188:191], v[132:135]
	v_mfma_f32_16x16x32_bf16 v[108:111], v[172:175], v[188:191], v[108:111]
	v_mfma_f32_16x16x32_bf16 v[76:79], v[180:183], v[188:191], v[76:79]
	v_mfma_f32_16x16x32_bf16 v[40:43], v[184:187], v[188:191], v[40:43]
	ds_read_b128 v[188:191], v152 offset:56832
	ds_write_b128 v230, v[212:215] offset:12384
	global_load_dwordx4 v[212:215], v156, s[100:101] offset:2112
	s_waitcnt lgkmcnt(3)
	v_mfma_f32_16x16x32_bf16 v[124:127], v[168:171], v[176:179], v[124:127]
	v_mfma_f32_16x16x32_bf16 v[96:99], v[172:175], v[176:179], v[96:99]
	v_mfma_f32_16x16x32_bf16 v[64:67], v[180:183], v[176:179], v[64:67]
	v_mfma_f32_16x16x32_bf16 v[12:15], v[184:187], v[176:179], v[12:15]
	ds_read_b128 v[176:179], v152 offset:58368
	ds_write_b128 v230, v[220:223] offset:12480
	global_load_dwordx4 v[220:223], v156, s[100:101] offset:2176
	s_waitcnt lgkmcnt(3)
	v_mfma_f32_16x16x32_bf16 v[116:119], v[168:171], v[188:191], v[116:119]
	v_mfma_f32_16x16x32_bf16 v[84:87], v[172:175], v[188:191], v[84:87]
	v_mfma_f32_16x16x32_bf16 v[56:59], v[180:183], v[188:191], v[56:59]
	v_mfma_f32_16x16x32_bf16 v[8:11], v[184:187], v[188:191], v[8:11]
	ds_read_b128 v[188:191], v152 offset:59904
	ds_write_b128 v230, v[224:227] offset:12576
	global_load_dwordx4 v[224:227], v156, s[100:101] offset:2240
	s_waitcnt lgkmcnt(3)
	v_mfma_f32_16x16x32_bf16 v[104:107], v[168:171], v[176:179], v[104:107]
	v_mfma_f32_16x16x32_bf16 v[72:75], v[172:175], v[176:179], v[72:75]
	v_mfma_f32_16x16x32_bf16 v[52:55], v[180:183], v[176:179], v[52:55]
	v_mfma_f32_16x16x32_bf16 v[4:7], v[184:187], v[176:179], v[4:7]
	s_add_u32 s98, s98, s16
	s_addc_u32 s99, s99, s17
	s_add_u32 s100, s100, s14
	s_addc_u32 s101, s101, s15
	s_add_i32 s33, s33, 2
	s_waitcnt lgkmcnt(1)
	v_mfma_f32_16x16x32_bf16 v[92:95], v[168:171], v[188:191], v[92:95]
	v_mfma_f32_16x16x32_bf16 v[60:63], v[172:175], v[188:191], v[60:63]
	v_mfma_f32_16x16x32_bf16 v[48:51], v[180:183], v[188:191], v[48:51]
	v_mfma_f32_16x16x32_bf16 v[0:3], v[184:187], v[188:191], v[0:3]
	s_setprio 0
	s_cmpk_lg_i32 s33, 85
	s_waitcnt lgkmcnt(0)
	s_barrier
	s_cbranch_scc1 .LBB0_1095
	s_setprio 1
	ds_read_b128 v[168:171], v228 offset:0
	ds_read_b128 v[172:175], v228 offset:1536
	ds_read_b128 v[180:183], v228 offset:3072
	ds_read_b128 v[184:187], v228 offset:4608
	ds_read_b128 v[176:179], v152 offset:12288
	ds_read_b128 v[188:191], v152 offset:13824
	s_waitcnt lgkmcnt(1)
	v_mfma_f32_16x16x32_bf16 v[148:151], v[168:171], v[176:179], v[148:151]
	v_mfma_f32_16x16x32_bf16 v[136:139], v[172:175], v[176:179], v[136:139]
	v_mfma_f32_16x16x32_bf16 v[112:115], v[180:183], v[176:179], v[112:115]
	v_mfma_f32_16x16x32_bf16 v[80:83], v[184:187], v[176:179], v[80:83]
	ds_read_b128 v[176:179], v152 offset:15360
	s_waitcnt vmcnt(6)
	ds_write_b128 v229, v[20:23] offset:36864
	s_waitcnt lgkmcnt(2)
	v_mfma_f32_16x16x32_bf16 v[144:147], v[168:171], v[188:191], v[144:147]
	v_mfma_f32_16x16x32_bf16 v[128:131], v[172:175], v[188:191], v[128:131]
	v_mfma_f32_16x16x32_bf16 v[100:103], v[180:183], v[188:191], v[100:103]
	v_mfma_f32_16x16x32_bf16 v[68:71], v[184:187], v[188:191], v[68:71]
	ds_read_b128 v[188:191], v152 offset:16896
	ds_write_b128 v229, v[16:19] offset:36960
	global_load_dwordx4 v[20:23], v154, s[98:99]
	global_load_dwordx4 v[16:19], v154, s[98:99] offset:64
	s_waitcnt lgkmcnt(3)
	v_mfma_f32_16x16x32_bf16 v[140:143], v[168:171], v[176:179], v[140:143]
	v_mfma_f32_16x16x32_bf16 v[120:123], v[172:175], v[176:179], v[120:123]
	v_mfma_f32_16x16x32_bf16 v[88:91], v[180:183], v[176:179], v[88:91]
	v_mfma_f32_16x16x32_bf16 v[44:47], v[184:187], v[176:179], v[44:47]
	ds_read_b128 v[176:179], v152 offset:18432
	ds_write_b128 v230, v[36:39] offset:49152
	global_load_dwordx4 v[36:39], v156, s[100:101] offset:2048
	s_waitcnt lgkmcnt(3)
	v_mfma_f32_16x16x32_bf16 v[132:135], v[168:171], v[188:191], v[132:135]
	v_mfma_f32_16x16x32_bf16 v[108:111], v[172:175], v[188:191], v[108:111]
	v_mfma_f32_16x16x32_bf16 v[76:79], v[180:183], v[188:191], v[76:79]
	v_mfma_f32_16x16x32_bf16 v[40:43], v[184:187], v[188:191], v[40:43]
	ds_read_b128 v[188:191], v152 offset:19968
	ds_write_b128 v230, v[32:35] offset:49248
	global_load_dwordx4 v[32:35], v156, s[100:101] offset:2112
	s_waitcnt lgkmcnt(3)
	v_mfma_f32_16x16x32_bf16 v[124:127], v[168:171], v[176:179], v[124:127]
	v_mfma_f32_16x16x32_bf16 v[96:99], v[172:175], v[176:179], v[96:99]
	v_mfma_f32_16x16x32_bf16 v[64:67], v[180:183], v[176:179], v[64:67]
	v_mfma_f32_16x16x32_bf16 v[12:15], v[184:187], v[176:179], v[12:15]
	ds_read_b128 v[176:179], v152 offset:21504
	ds_write_b128 v230, v[28:31] offset:49344
	global_load_dwordx4 v[28:31], v156, s[100:101] offset:2176
	s_waitcnt lgkmcnt(3)
	v_mfma_f32_16x16x32_bf16 v[116:119], v[168:171], v[188:191], v[116:119]
	v_mfma_f32_16x16x32_bf16 v[84:87], v[172:175], v[188:191], v[84:87]
	v_mfma_f32_16x16x32_bf16 v[56:59], v[180:183], v[188:191], v[56:59]
	v_mfma_f32_16x16x32_bf16 v[8:11], v[184:187], v[188:191], v[8:11]
	ds_read_b128 v[188:191], v152 offset:23040
	ds_write_b128 v230, v[24:27] offset:49440
	global_load_dwordx4 v[24:27], v156, s[100:101] offset:2240
	s_waitcnt lgkmcnt(3)
	v_mfma_f32_16x16x32_bf16 v[104:107], v[168:171], v[176:179], v[104:107]
	v_mfma_f32_16x16x32_bf16 v[72:75], v[172:175], v[176:179], v[72:75]
	v_mfma_f32_16x16x32_bf16 v[52:55], v[180:183], v[176:179], v[52:55]
	v_mfma_f32_16x16x32_bf16 v[4:7], v[184:187], v[176:179], v[4:7]
	s_add_u32 s98, s98, s16
	s_addc_u32 s99, s99, s17
	s_add_u32 s100, s100, s14
	s_addc_u32 s101, s101, s15
	s_waitcnt lgkmcnt(1)
	v_mfma_f32_16x16x32_bf16 v[92:95], v[168:171], v[188:191], v[92:95]
	v_mfma_f32_16x16x32_bf16 v[60:63], v[172:175], v[188:191], v[60:63]
	v_mfma_f32_16x16x32_bf16 v[48:51], v[180:183], v[188:191], v[48:51]
	v_mfma_f32_16x16x32_bf16 v[0:3], v[184:187], v[188:191], v[0:3]
	s_setprio 0
	s_waitcnt lgkmcnt(0)
	s_barrier
; DI f32x4 mfma16(bf16x8 a, bf16x8 b, f32x4 c) { return __builtin_amdgcn_mfma_f32_16x16x32_bf16(a, b, c, 0, 0, 0); }
; template <int NI, class XL, class EP>
; DI void gemm_tile(const u16* __restrict__ W, int ldw, int f0, int t0, int K, XL xl, EP ep, unsigned char* smem) {
;     ...
;   for (int it = 0; it < nk; ++it) {
;     const u16* Ws = S0 + (it & 1) * BUF; const u16* Xs = Ws + 128 * LST;
;     __builtin_amdgcn_s_setprio(1);
;     bf16x8 a[4];
; #pragma unroll
;     for (int mi = 0; mi < 4; ++mi) a[mi] = *(const bf16x8*)(Ws + (wf * 64 + mi * 16 + lr) * LST + lq * 8);
; #pragma unroll
;     for (int ni = 0; ni < NI; ++ni) {
;       const bf16x8 b = *(const bf16x8*)(Xs + (wt * (NI * 16) + ni * 16 + lr) * LST + lq * 8);
; #pragma unroll
;       for (int mi = 0; mi < 4; ++mi) acc[mi][ni] = mfma16(a[mi], b, acc[mi][ni]);
;     }
;     __builtin_amdgcn_sched_group_barrier(0x100, 6, 0);
; #pragma unroll
;     for (int ni = 0; ni < NI; ++ni) { __builtin_amdgcn_sched_group_barrier(0x008, 4, 0); if (ni + 2 < NI) __builtin_amdgcn_sched_group_barrier(0x100, 1, 0); }
;     __builtin_amdgcn_s_setprio(0);
;     if (it + 1 < nk) lstore((it + 1) & 1);
;     if (it + 2 < nk) gload(it + 2);
;     __syncthreads();
;   }
	s_setprio 1
	ds_read_b128 v[168:171], v228 offset:36864
	ds_read_b128 v[172:175], v228 offset:38400
	ds_read_b128 v[180:183], v228 offset:39936
	ds_read_b128 v[184:187], v228 offset:41472
	ds_read_b128 v[176:179], v152 offset:49152
	ds_read_b128 v[188:191], v152 offset:50688
	s_waitcnt lgkmcnt(1)
	v_mfma_f32_16x16x32_bf16 v[148:151], v[168:171], v[176:179], v[148:151]
	v_mfma_f32_16x16x32_bf16 v[136:139], v[172:175], v[176:179], v[136:139]
	v_mfma_f32_16x16x32_bf16 v[112:115], v[180:183], v[176:179], v[112:115]
	v_mfma_f32_16x16x32_bf16 v[80:83], v[184:187], v[176:179], v[80:83]
	ds_read_b128 v[176:179], v152 offset:52224
	s_waitcnt vmcnt(6)
	ds_write_b128 v229, v[200:203] offset:0
	s_waitcnt lgkmcnt(2)
	v_mfma_f32_16x16x32_bf16 v[144:147], v[168:171], v[188:191], v[144:147]
	v_mfma_f32_16x16x32_bf16 v[128:131], v[172:175], v[188:191], v[128:131]
	v_mfma_f32_16x16x32_bf16 v[100:103], v[180:183], v[188:191], v[100:103]
	v_mfma_f32_16x16x32_bf16 v[68:71], v[184:187], v[188:191], v[68:71]
	ds_read_b128 v[188:191], v152 offset:53760
	ds_write_b128 v229, v[204:207] offset:96
	s_waitcnt lgkmcnt(3)
	v_mfma_f32_16x16x32_bf16 v[140:143], v[168:171], v[176:179], v[140:143]
	v_mfma_f32_16x16x32_bf16 v[120:123], v[172:175], v[176:179], v[120:123]
	v_mfma_f32_16x16x32_bf16 v[88:91], v[180:183], v[176:179], v[88:91]
	v_mfma_f32_16x16x32_bf16 v[44:47], v[184:187], v[176:179], v[44:47]
	ds_read_b128 v[176:179], v152 offset:55296
	ds_write_b128 v230, v[208:211] offset:12288
	s_waitcnt lgkmcnt(3)
	v_mfma_f32_16x16x32_bf16 v[132:135], v[168:171], v[188:191], v[132:135]
	v_mfma_f32_16x16x32_bf16 v[108:111], v[172:175], v[188:191], v[108:111]
	v_mfma_f32_16x16x32_bf16 v[76:79], v[180:183], v[188:191], v[76:79]
	v_mfma_f32_16x16x32_bf16 v[40:43], v[184:187], v[188:191], v[40:43]
	ds_read_b128 v[188:191], v152 offset:56832
	ds_write_b128 v230, v[212:215] offset:12384
	s_waitcnt lgkmcnt(3)
	v_mfma_f32_16x16x32_bf16 v[124:127], v[168:171], v[176:179], v[124:127]
	v_mfma_f32_16x16x32_bf16 v[96:99], v[172:175], v[176:179], v[96:99]
	v_mfma_f32_16x16x32_bf16 v[64:67], v[180:183], v[176:179], v[64:67]
	v_mfma_f32_16x16x32_bf16 v[12:15], v[184:187], v[176:179], v[12:15]
	ds_read_b128 v[176:179], v152 offset:58368
	ds_write_b128 v230, v[220:223] offset:12480
	s_waitcnt lgkmcnt(3)
	v_mfma_f32_16x16x32_bf16 v[116:119], v[168:171], v[188:191], v[116:119]
	v_mfma_f32_16x16x32_bf16 v[84:87], v[172:175], v[188:191], v[84:87]
	v_mfma_f32_16x16x32_bf16 v[56:59], v[180:183], v[188:191], v[56:59]
	v_mfma_f32_16x16x32_bf16 v[8:11], v[184:187], v[188:191], v[8:11]
	ds_read_b128 v[188:191], v152 offset:59904
	ds_write_b128 v230, v[224:227] offset:12576
	s_waitcnt lgkmcnt(3)
	v_mfma_f32_16x16x32_bf16 v[104:107], v[168:171], v[176:179], v[104:107]
	v_mfma_f32_16x16x32_bf16 v[72:75], v[172:175], v[176:179], v[72:75]
	v_mfma_f32_16x16x32_bf16 v[52:55], v[180:183], v[176:179], v[52:55]
	v_mfma_f32_16x16x32_bf16 v[4:7], v[184:187], v[176:179], v[4:7]
	s_add_i32 s33, s33, 2
	s_waitcnt lgkmcnt(1)
	v_mfma_f32_16x16x32_bf16 v[92:95], v[168:171], v[188:191], v[92:95]
	v_mfma_f32_16x16x32_bf16 v[60:63], v[172:175], v[188:191], v[60:63]
	v_mfma_f32_16x16x32_bf16 v[48:51], v[180:183], v[188:191], v[48:51]
	v_mfma_f32_16x16x32_bf16 v[0:3], v[184:187], v[188:191], v[0:3]
	s_setprio 0
	s_waitcnt lgkmcnt(0)
	s_barrier
	s_setprio 1
	v_lshl_add_u32 v152, v167, 1, v164
	ds_read_b128 v[154:157], v152
	v_lshl_add_u32 v161, v165, 1, v164
	ds_read_b128 v[164:167], v152 offset:1536
	ds_read_b128 v[172:175], v152 offset:3072
	ds_read_b128 v[176:179], v152 offset:4608
	ds_read_b128 v[168:171], v161 offset:12288
	ds_read_b128 v[180:183], v161 offset:13824
	s_waitcnt lgkmcnt(1)
	v_mfma_f32_16x16x32_bf16 v[148:151], v[154:157], v[168:171], v[148:151]
	v_mfma_f32_16x16x32_bf16 v[136:139], v[164:167], v[168:171], v[136:139]
	v_mfma_f32_16x16x32_bf16 v[112:115], v[172:175], v[168:171], v[112:115]
	v_mfma_f32_16x16x32_bf16 v[80:83], v[176:179], v[168:171], v[80:83]
	ds_read_b128 v[168:171], v161 offset:15360
	s_waitcnt vmcnt(5)
	ds_write_b128 v162, v[20:23] offset:36864
	s_waitcnt lgkmcnt(2)
	v_mfma_f32_16x16x32_bf16 v[144:147], v[154:157], v[180:183], v[144:147]
	v_mfma_f32_16x16x32_bf16 v[128:131], v[164:167], v[180:183], v[128:131]
	v_mfma_f32_16x16x32_bf16 v[100:103], v[172:175], v[180:183], v[100:103]
	v_mfma_f32_16x16x32_bf16 v[68:71], v[176:179], v[180:183], v[68:71]
	ds_read_b128 v[180:183], v161 offset:16896
	s_waitcnt vmcnt(4)
	ds_write_b128 v162, v[16:19] offset:36960
	s_waitcnt lgkmcnt(3)
	v_mfma_f32_16x16x32_bf16 v[140:143], v[154:157], v[168:171], v[140:143]
	v_mfma_f32_16x16x32_bf16 v[120:123], v[164:167], v[168:171], v[120:123]
	v_mfma_f32_16x16x32_bf16 v[184:187], v[172:175], v[168:171], v[88:91]
	v_mfma_f32_16x16x32_bf16 v[44:47], v[176:179], v[168:171], v[44:47]
	s_nop 1
	ds_read_b128 v[88:91], v161 offset:18432
	s_waitcnt vmcnt(3)
	ds_write_b128 v163, v[36:39] offset:49152
	s_waitcnt lgkmcnt(3)
	v_mfma_f32_16x16x32_bf16 v[132:135], v[154:157], v[180:183], v[132:135]
	v_mfma_f32_16x16x32_bf16 v[168:171], v[164:167], v[180:183], v[108:111]
	v_mfma_f32_16x16x32_bf16 v[188:191], v[172:175], v[180:183], v[76:79]
	v_mfma_f32_16x16x32_bf16 v[180:183], v[176:179], v[180:183], v[40:43]
	s_nop 2
	ds_read_b128 v[40:43], v161 offset:19968
	s_waitcnt vmcnt(2)
	ds_write_b128 v163, v[32:35] offset:49248
	s_waitcnt lgkmcnt(3)
	v_mfma_f32_16x16x32_bf16 v[124:127], v[154:157], v[88:91], v[124:127]
	v_mfma_f32_16x16x32_bf16 v[192:195], v[164:167], v[88:91], v[96:99]
	v_mfma_f32_16x16x32_bf16 v[196:199], v[172:175], v[88:91], v[64:67]
	v_mfma_f32_16x16x32_bf16 v[200:203], v[176:179], v[88:91], v[12:15]
	s_nop 2
	ds_read_b128 v[12:15], v161 offset:21504
	s_waitcnt vmcnt(1)
	ds_write_b128 v163, v[28:31] offset:49344
	s_waitcnt lgkmcnt(3)
	v_mfma_f32_16x16x32_bf16 v[116:119], v[154:157], v[40:43], v[116:119]
	v_mfma_f32_16x16x32_bf16 v[204:207], v[164:167], v[40:43], v[84:87]
	v_mfma_f32_16x16x32_bf16 v[56:59], v[172:175], v[40:43], v[56:59]
	v_mfma_f32_16x16x32_bf16 v[208:211], v[176:179], v[40:43], v[8:11]
	s_nop 2
	ds_read_b128 v[8:11], v161 offset:23040
	s_waitcnt vmcnt(0)
	ds_write_b128 v163, v[24:27] offset:49440
	s_waitcnt lgkmcnt(3)
	v_mfma_f32_16x16x32_bf16 v[212:215], v[154:157], v[12:15], v[104:107]
	v_mfma_f32_16x16x32_bf16 v[72:75], v[164:167], v[12:15], v[72:75]
	v_mfma_f32_16x16x32_bf16 v[220:223], v[172:175], v[12:15], v[52:55]
	v_mfma_f32_16x16x32_bf16 v[224:227], v[176:179], v[12:15], v[4:7]
	s_waitcnt lgkmcnt(1)
	v_mfma_f32_16x16x32_bf16 v[154:157], v[154:157], v[8:11], v[92:95]
	v_mfma_f32_16x16x32_bf16 v[60:63], v[164:167], v[8:11], v[60:63]
	v_mfma_f32_16x16x32_bf16 v[164:167], v[172:175], v[8:11], v[48:51]
	v_mfma_f32_16x16x32_bf16 v[172:175], v[176:179], v[8:11], v[0:3]
	s_setprio 0
	s_waitcnt lgkmcnt(0)
	s_barrier
; DI void store4(u16* dst, f32x4 v) { uint2 w; w.x = cvtpk(v[0], v[1]); w.y = cvtpk(v[2], v[3]); *(uint2*)dst = w; }
; DI f32x4 mfma16(bf16x8 a, bf16x8 b, f32x4 c) { return __builtin_amdgcn_mfma_f32_16x16x32_bf16(a, b, c, 0, 0, 0); }
; template <int NI, class XL, class EP>
; DI void gemm_tile(const u16* __restrict__ W, int ldw, int f0, int t0, int K, XL xl, EP ep, unsigned char* smem) {
;     ...
;     for (int mi = 0; mi < 4; ++mi) a[mi] = *(const bf16x8*)(Ws + (wf * 64 + mi * 16 + lr) * LST + lq * 8);
; #pragma unroll
;     for (int ni = 0; ni < NI; ++ni) {
;       const bf16x8 b = *(const bf16x8*)(Xs + (wt * (NI * 16) + ni * 16 + lr) * LST + lq * 8);
; #pragma unroll
;       for (int mi = 0; mi < 4; ++mi) acc[mi][ni] = mfma16(a[mi], b, acc[mi][ni]);
;     }
;     __builtin_amdgcn_sched_group_barrier(0x100, 6, 0);
; #pragma unroll
;     for (int ni = 0; ni < NI; ++ni) { __builtin_amdgcn_sched_group_barrier(0x008, 4, 0); if (ni + 2 < NI) __builtin_amdgcn_sched_group_barrier(0x100, 1, 0); }
;     __builtin_amdgcn_s_setprio(0);
; DI void phase6(const Params& p, const Sched& sched, unsigned char* smem) {
;     ...
;       const int b = tb >> 11;
;       __syncthreads();
; #pragma unroll
;       for (int mi = 0; mi < 4; ++mi) {
;         const int f = fb + mi * 16 + lq * 4; const float4 gm = *(const float4*)(mod + (size_t)b * 6144 + 2048 + f);
; #pragma unroll
;         for (int ni = 0; ni < 8; ++ni) {
;           const f32x4 o = {gm.x * acc[mi][ni][0], gm.y * acc[mi][ni][1], gm.z * acc[mi][ni][2], gm.w * acc[mi][ni][3]};
;           store4(Ls + (wt * 128 + ni * 16 + lr) * EST + wf * 64 + mi * 16 + lq * 4, o);
;         }
;       }
	s_lshl_b32 s30, s30, 7
	s_setprio 1
	ds_read_b128 v[28:31], v152 offset:36864
	ds_read_b128 v[176:179], v152 offset:38400
	ds_read_b128 v[228:231], v152 offset:39936
	ds_read_b128 v[232:235], v152 offset:41472
	ds_read_b128 v[0:3], v161 offset:49152
	ds_read_b128 v[4:7], v161 offset:50688
	s_waitcnt lgkmcnt(1)
	v_mfma_f32_16x16x32_bf16 v[88:91], v[28:31], v[0:3], v[148:151]
	v_mfma_f32_16x16x32_bf16 v[64:67], v[176:179], v[0:3], v[136:139]
	v_mfma_f32_16x16x32_bf16 v[32:35], v[228:231], v[0:3], v[112:115]
	v_mfma_f32_16x16x32_bf16 v[0:3], v[232:235], v[0:3], v[80:83]
	ds_read_b128 v[8:11], v161 offset:52224
	s_waitcnt lgkmcnt(1)
	v_mfma_f32_16x16x32_bf16 v[96:99], v[28:31], v[4:7], v[144:147]
	v_mfma_f32_16x16x32_bf16 v[76:79], v[176:179], v[4:7], v[128:131]
	v_mfma_f32_16x16x32_bf16 v[36:39], v[228:231], v[4:7], v[100:103]
	v_mfma_f32_16x16x32_bf16 v[4:7], v[232:235], v[4:7], v[68:71]
	ds_read_b128 v[12:15], v161 offset:53760
	s_waitcnt lgkmcnt(1)
	v_mfma_f32_16x16x32_bf16 v[104:107], v[28:31], v[8:11], v[140:143]
	v_mfma_f32_16x16x32_bf16 v[84:87], v[176:179], v[8:11], v[120:123]
	v_mfma_f32_16x16x32_bf16 v[40:43], v[228:231], v[8:11], v[184:187]
	v_mfma_f32_16x16x32_bf16 v[8:11], v[232:235], v[8:11], v[44:47]
	ds_read_b128 v[16:19], v161 offset:55296
	s_waitcnt lgkmcnt(1)
	v_mfma_f32_16x16x32_bf16 v[108:111], v[28:31], v[12:15], v[132:135]
	v_mfma_f32_16x16x32_bf16 v[92:95], v[176:179], v[12:15], v[168:171]
	v_mfma_f32_16x16x32_bf16 v[44:47], v[228:231], v[12:15], v[188:191]
	v_mfma_f32_16x16x32_bf16 v[12:15], v[232:235], v[12:15], v[180:183]
	ds_read_b128 v[20:23], v161 offset:56832
	s_waitcnt lgkmcnt(1)
	v_mfma_f32_16x16x32_bf16 v[112:115], v[28:31], v[16:19], v[124:127]
	v_mfma_f32_16x16x32_bf16 v[100:103], v[176:179], v[16:19], v[192:195]
	v_mfma_f32_16x16x32_bf16 v[48:51], v[228:231], v[16:19], v[196:199]
	v_mfma_f32_16x16x32_bf16 v[16:19], v[232:235], v[16:19], v[200:203]
	ds_read_b128 v[24:27], v161 offset:58368
	s_waitcnt lgkmcnt(1)
	v_mfma_f32_16x16x32_bf16 v[116:119], v[28:31], v[20:23], v[116:119]
	v_mfma_f32_16x16x32_bf16 v[68:71], v[176:179], v[20:23], v[204:207]
	v_mfma_f32_16x16x32_bf16 v[52:55], v[228:231], v[20:23], v[56:59]
	v_mfma_f32_16x16x32_bf16 v[20:23], v[232:235], v[20:23], v[208:211]
	ds_read_b128 v[128:131], v161 offset:59904
	s_waitcnt lgkmcnt(1)
	v_mfma_f32_16x16x32_bf16 v[120:123], v[28:31], v[24:27], v[212:215]
	v_mfma_f32_16x16x32_bf16 v[80:83], v[176:179], v[24:27], v[72:75]
	v_mfma_f32_16x16x32_bf16 v[56:59], v[228:231], v[24:27], v[220:223]
	v_mfma_f32_16x16x32_bf16 v[24:27], v[232:235], v[24:27], v[224:227]
	s_waitcnt lgkmcnt(0)
	v_mfma_f32_16x16x32_bf16 v[124:127], v[28:31], v[128:131], v[154:157]
	v_mfma_f32_16x16x32_bf16 v[72:75], v[176:179], v[128:131], v[60:63]
	v_mfma_f32_16x16x32_bf16 v[60:63], v[228:231], v[128:131], v[164:167]
	v_mfma_f32_16x16x32_bf16 v[28:31], v[232:235], v[128:131], v[172:175]
	s_setprio 0
	s_ashr_i32 s31, s31, 3
	v_add_u32_e32 v128, s30, v160
	s_mul_hi_i32 s33, s31, 0x6000
	s_mulk_i32 s31, 0x6000
	v_lshl_or_b32 v128, v158, 2, v128
	s_add_u32 s34, s72, s31
	s_addc_u32 s35, s73, s33
	v_ashrrev_i32_e32 v129, 31, v128
	v_lshl_add_u64 v[128:129], v[128:129], 2, s[34:35]
	v_add_co_u32_e32 v140, vcc, s24, v128
	v_mul_u32_u24_e32 v138, 0x88, v159
	s_nop 0
	v_addc_co_u32_e32 v141, vcc, 0, v129, vcc
	v_lshlrev_b32_e32 v136, 1, v160
	v_lshlrev_b32_e32 v137, 3, v158
	v_lshlrev_b32_e32 v138, 1, v138
	s_barrier
	global_load_dwordx4 v[128:131], v[140:141], off
	global_load_dwordx4 v[132:135], v[140:141], off offset:64
	v_add3_u32 v144, v136, v137, v138
	global_load_dwordx4 v[136:139], v[140:141], off offset:128
	v_add_u32_e32 v145, 0x1000, v144
	global_load_dwordx4 v[140:143], v[140:141], off offset:192
	v_add_u32_e32 v146, 0x2000, v144
	v_add_u32_e32 v147, 0x3000, v144
	v_add_u32_e32 v148, 0x4000, v144
	s_add_i32 s28, s28, s78
	s_add_i32 s27, s27, s78
	s_cmp_gt_i32 s28, 63
	s_waitcnt vmcnt(3)
	v_pk_mul_f32 v[88:89], v[88:89], v[128:129]
	v_pk_mul_f32 v[90:91], v[90:91], v[130:131]
	v_pk_mul_f32 v[96:97], v[96:97], v[128:129]
	s_waitcnt vmcnt(1)
	v_pk_mul_f32 v[32:33], v[32:33], v[136:137]
	v_pk_mul_f32 v[34:35], v[34:35], v[138:139]
	s_waitcnt vmcnt(0)
	v_pk_mul_f32 v[0:1], v[0:1], v[140:141]
	v_pk_mul_f32 v[2:3], v[2:3], v[142:143]
	v_cvt_pk_bf16_f32 v32, v32, v33
	v_cvt_pk_bf16_f32 v33, v34, v35
	v_cvt_pk_bf16_f32 v0, v0, v1
	v_cvt_pk_bf16_f32 v1, v2, v3
	v_pk_mul_f32 v[34:35], v[36:37], v[136:137]
	v_pk_mul_f32 v[36:37], v[38:39], v[138:139]
	ds_write2_b64 v144, v[32:33], v[0:1] offset0:8 offset1:12
	v_pk_mul_f32 v[0:1], v[4:5], v[140:141]
	v_pk_mul_f32 v[2:3], v[6:7], v[142:143]
	v_cvt_pk_bf16_f32 v34, v34, v35
	v_cvt_pk_bf16_f32 v35, v36, v37
	v_cvt_pk_bf16_f32 v0, v0, v1
	v_cvt_pk_bf16_f32 v1, v2, v3
	v_pk_mul_f32 v[36:37], v[40:41], v[136:137]
	v_pk_mul_f32 v[38:39], v[42:43], v[138:139]
	ds_write2_b64 v145, v[34:35], v[0:1] offset0:40 offset1:44
	v_pk_mul_f32 v[0:1], v[8:9], v[140:141]
	v_pk_mul_f32 v[2:3], v[10:11], v[142:143]
	v_cvt_pk_bf16_f32 v36, v36, v37
	v_cvt_pk_bf16_f32 v37, v38, v39
	v_cvt_pk_bf16_f32 v0, v0, v1
	v_cvt_pk_bf16_f32 v1, v2, v3
	v_pk_mul_f32 v[38:39], v[44:45], v[136:137]
	v_pk_mul_f32 v[40:41], v[46:47], v[138:139]
	ds_write2_b64 v146, v[36:37], v[0:1] offset0:72 offset1:76
	v_pk_mul_f32 v[0:1], v[12:13], v[140:141]
	v_pk_mul_f32 v[2:3], v[14:15], v[142:143]
	v_cvt_pk_bf16_f32 v38, v38, v39
	v_cvt_pk_bf16_f32 v39, v40, v41
	v_cvt_pk_bf16_f32 v0, v0, v1
	v_cvt_pk_bf16_f32 v1, v2, v3
	v_pk_mul_f32 v[98:99], v[98:99], v[130:131]
	v_pk_mul_f32 v[64:65], v[64:65], v[132:133]
	v_pk_mul_f32 v[66:67], v[66:67], v[134:135]
	v_pk_mul_f32 v[76:77], v[76:77], v[132:133]
; DI void store4(u16* dst, f32x4 v) { uint2 w; w.x = cvtpk(v[0], v[1]); w.y = cvtpk(v[2], v[3]); *(uint2*)dst = w; }
; DI void phase9(const Params& p, const Sched& sched, unsigned char* smem) {
;     ...
; #pragma unroll
;       for (int mi = 0; mi < 4; ++mi) {
;         const int f = fb + mi * 16 + lq * 4; const float4 gm = *(const float4*)(mod + (size_t)b * 6144 + 5120 + f);
; #pragma unroll
;         for (int ni = 0; ni < 8; ++ni) {
;           const f32x4 o = {gm.x * acc[mi][ni][0], gm.y * acc[mi][ni][1], gm.z * acc[mi][ni][2], gm.w * acc[mi][ni][3]};
;           store4(Ls + (wt * 128 + ni * 16 + lr) * EST + wf * 64 + mi * 16 + lq * 4, o);
;         }
;       }
;       __syncthreads();
	v_pk_mul_f32 v[78:79], v[78:79], v[134:135]
	v_pk_mul_f32 v[40:41], v[48:49], v[136:137]
	v_pk_mul_f32 v[42:43], v[50:51], v[138:139]
	ds_write2_b64 v147, v[38:39], v[0:1] offset0:104 offset1:108
	v_pk_mul_f32 v[0:1], v[16:17], v[140:141]
	v_pk_mul_f32 v[2:3], v[18:19], v[142:143]
	v_cvt_pk_bf16_f32 v88, v88, v89
	v_cvt_pk_bf16_f32 v89, v90, v91
	v_cvt_pk_bf16_f32 v90, v96, v97
	v_cvt_pk_bf16_f32 v91, v98, v99
	v_cvt_pk_bf16_f32 v64, v64, v65
	v_cvt_pk_bf16_f32 v65, v66, v67
	v_cvt_pk_bf16_f32 v66, v76, v77
	v_cvt_pk_bf16_f32 v67, v78, v79
	v_cvt_pk_bf16_f32 v40, v40, v41
	v_cvt_pk_bf16_f32 v41, v42, v43
	v_cvt_pk_bf16_f32 v0, v0, v1
	v_cvt_pk_bf16_f32 v1, v2, v3
	v_pk_mul_f32 v[106:107], v[106:107], v[130:131]
	v_pk_mul_f32 v[116:117], v[116:117], v[128:129]
	v_pk_mul_f32 v[118:119], v[118:119], v[130:131]
	ds_write2_b64 v144, v[88:89], v[64:65] offset1:4
	ds_write2_b64 v145, v[90:91], v[66:67] offset0:32 offset1:36
	v_pk_mul_f32 v[64:65], v[68:69], v[132:133]
	v_pk_mul_f32 v[66:67], v[70:71], v[134:135]
	v_pk_mul_f32 v[42:43], v[52:53], v[136:137]
	v_pk_mul_f32 v[44:45], v[54:55], v[138:139]
	ds_write2_b64 v148, v[40:41], v[0:1] offset0:136 offset1:140
	v_pk_mul_f32 v[0:1], v[20:21], v[140:141]
	v_pk_mul_f32 v[2:3], v[22:23], v[142:143]
	v_cvt_pk_bf16_f32 v97, v106, v107
	v_cvt_pk_bf16_f32 v106, v116, v117
	v_cvt_pk_bf16_f32 v107, v118, v119
	v_cvt_pk_bf16_f32 v64, v64, v65
	v_cvt_pk_bf16_f32 v65, v66, v67
	v_add_u32_e32 v68, 0x5000, v144
	v_cvt_pk_bf16_f32 v42, v42, v43
	v_cvt_pk_bf16_f32 v43, v44, v45
	v_cvt_pk_bf16_f32 v0, v0, v1
	v_cvt_pk_bf16_f32 v1, v2, v3
	v_pk_mul_f32 v[108:109], v[108:109], v[128:129]
	v_pk_mul_f32 v[120:121], v[120:121], v[128:129]
	v_pk_mul_f32 v[122:123], v[122:123], v[130:131]
	ds_write2_b64 v68, v[106:107], v[64:65] offset0:160 offset1:164
	v_pk_mul_f32 v[64:65], v[80:81], v[132:133]
	v_pk_mul_f32 v[66:67], v[82:83], v[134:135]
	v_pk_mul_f32 v[44:45], v[56:57], v[136:137]
	v_pk_mul_f32 v[46:47], v[58:59], v[138:139]
	ds_write2_b64 v68, v[42:43], v[0:1] offset0:168 offset1:172
	v_pk_mul_f32 v[0:1], v[24:25], v[140:141]
	v_pk_mul_f32 v[2:3], v[26:27], v[142:143]
	v_cvt_pk_bf16_f32 v98, v108, v109
	v_cvt_pk_bf16_f32 v108, v120, v121
	v_cvt_pk_bf16_f32 v109, v122, v123
	v_cvt_pk_bf16_f32 v64, v64, v65
	v_cvt_pk_bf16_f32 v65, v66, v67
	v_add_u32_e32 v69, 0x6000, v144
	v_cvt_pk_bf16_f32 v44, v44, v45
	v_cvt_pk_bf16_f32 v45, v46, v47
	v_cvt_pk_bf16_f32 v0, v0, v1
	v_cvt_pk_bf16_f32 v1, v2, v3
	v_pk_mul_f32 v[104:105], v[104:105], v[128:129]
	v_pk_mul_f32 v[110:111], v[110:111], v[130:131]
	v_pk_mul_f32 v[112:113], v[112:113], v[128:129]
	v_pk_mul_f32 v[114:115], v[114:115], v[130:131]
	v_pk_mul_f32 v[124:125], v[124:125], v[128:129]
	v_pk_mul_f32 v[126:127], v[126:127], v[130:131]
	v_pk_mul_f32 v[84:85], v[84:85], v[132:133]
	v_pk_mul_f32 v[86:87], v[86:87], v[134:135]
	v_pk_mul_f32 v[92:93], v[92:93], v[132:133]
	v_pk_mul_f32 v[94:95], v[94:95], v[134:135]
	v_pk_mul_f32 v[100:101], v[100:101], v[132:133]
	v_pk_mul_f32 v[102:103], v[102:103], v[134:135]
	ds_write2_b64 v69, v[108:109], v[64:65] offset0:192 offset1:196
	v_pk_mul_f32 v[64:65], v[72:73], v[132:133]
	v_pk_mul_f32 v[66:67], v[74:75], v[134:135]
	v_pk_mul_f32 v[46:47], v[60:61], v[136:137]
	v_pk_mul_f32 v[48:49], v[62:63], v[138:139]
	ds_write2_b64 v69, v[44:45], v[0:1] offset0:200 offset1:204
	v_pk_mul_f32 v[0:1], v[28:29], v[140:141]
	v_pk_mul_f32 v[2:3], v[30:31], v[142:143]
	v_cvt_pk_bf16_f32 v96, v104, v105
	v_cvt_pk_bf16_f32 v99, v110, v111
	v_cvt_pk_bf16_f32 v104, v112, v113
	v_cvt_pk_bf16_f32 v105, v114, v115
	v_cvt_pk_bf16_f32 v110, v124, v125
	v_cvt_pk_bf16_f32 v111, v126, v127
	v_cvt_pk_bf16_f32 v76, v84, v85
	v_cvt_pk_bf16_f32 v77, v86, v87
	v_cvt_pk_bf16_f32 v78, v92, v93
	v_cvt_pk_bf16_f32 v79, v94, v95
	v_cvt_pk_bf16_f32 v84, v100, v101
	v_cvt_pk_bf16_f32 v85, v102, v103
	v_cvt_pk_bf16_f32 v64, v64, v65
	v_cvt_pk_bf16_f32 v65, v66, v67
	v_add_u32_e32 v66, 0x7000, v144
	v_cvt_pk_bf16_f32 v46, v46, v47
	v_cvt_pk_bf16_f32 v47, v48, v49
	v_cvt_pk_bf16_f32 v0, v0, v1
	v_cvt_pk_bf16_f32 v1, v2, v3
	v_mov_b32_e32 v2, v218
	ds_write2_b64 v146, v[96:97], v[76:77] offset0:64 offset1:68
	ds_write2_b64 v147, v[98:99], v[78:79] offset0:96 offset1:100
	ds_write2_b64 v148, v[104:105], v[84:85] offset0:128 offset1:132
	ds_write2_b64 v66, v[110:111], v[64:65] offset0:224 offset1:228
	ds_write2_b64 v66, v[46:47], v[0:1] offset0:232 offset1:236
	s_waitcnt lgkmcnt(0)
	s_barrier
; DI int tidx() { int t = __builtin_amdgcn_workitem_id_x(); asm volatile("" : "+v"(t)); return t; }
; DI unsigned cvtpk(float lo, float hi) { const f32x2_ v = {lo, hi}; return __builtin_bit_cast(unsigned, __builtin_convertvector(v, bf16x2_)); }
; DI float bflo(unsigned w) { return __uint_as_float(w << 16); }
; DI float bfhi(unsigned w) { return __uint_as_float(w & 0xffff0000u); }
; DI void phase9(const Params& p, const Sched& sched, unsigned char* smem) {
;     ...
;       const int tid = tidx();
; #pragma unroll
;       for (int i = 0; i < 16; ++i) {
;         const int c = tid + 256 * i, row = c >> 4, ch = (c & 15) * 8;
;         const size_t gi = (size_t)(tm * 256 + row) * 1024 + tn * 128 + ch;
;         const u32x4 sv = *(const u32x4*)(Ls + row * EST + ch), xv = *(const u32x4*)(x1b + gi);
;         u32x4 w;
;         w.x = cvtpk(bflo(xv.x) + bflo(sv.x), bfhi(xv.x) + bfhi(sv.x)); w.y = cvtpk(bflo(xv.y) + bflo(sv.y), bfhi(xv.y) + bfhi(sv.y));
;         w.z = cvtpk(bflo(xv.z) + bflo(sv.z), bfhi(xv.z) + bfhi(sv.z)); w.w = cvtpk(bflo(xv.w) + bflo(sv.w), bfhi(xv.w) + bfhi(sv.w));
;         *(u32x4*)(x2b + gi) = w;
;       }
	v_ashrrev_i32_e32 v204, 4, v218
	v_lshlrev_b32_e32 v205, 3, v218
	v_and_b32_e32 v205, 0x78, v205
	v_add_u32_e32 v206, s29, v204
	v_ashrrev_i32_e32 v207, 31, v206
	v_lshlrev_b64 v[206:207], 10, v[206:207]
	v_or3_b32 v206, v206, s30, v205
	v_lshl_add_u64 v[200:201], v[206:207], 1, s[12:13]
	v_lshl_add_u64 v[202:203], v[206:207], 1, s[2:3]
	v_mul_u32_u24_e32 v204, 0x110, v204
	v_lshl_add_u32 v204, v205, 1, v204
	s_mov_b64 s[100:101], 0x8000
	global_load_dwordx4 v[0:3], v[200:201], off
	v_lshl_add_u64 v[200:201], v[200:201], 0, s[100:101]
	global_load_dwordx4 v[4:7], v[200:201], off
	v_lshl_add_u64 v[200:201], v[200:201], 0, s[100:101]
	global_load_dwordx4 v[8:11], v[200:201], off
	v_lshl_add_u64 v[200:201], v[200:201], 0, s[100:101]
	global_load_dwordx4 v[12:15], v[200:201], off
	v_lshl_add_u64 v[200:201], v[200:201], 0, s[100:101]
	global_load_dwordx4 v[16:19], v[200:201], off
	v_lshl_add_u64 v[200:201], v[200:201], 0, s[100:101]
	global_load_dwordx4 v[20:23], v[200:201], off
	v_lshl_add_u64 v[200:201], v[200:201], 0, s[100:101]
	global_load_dwordx4 v[24:27], v[200:201], off
	v_lshl_add_u64 v[200:201], v[200:201], 0, s[100:101]
	global_load_dwordx4 v[28:31], v[200:201], off
	v_lshl_add_u64 v[200:201], v[200:201], 0, s[100:101]
	global_load_dwordx4 v[32:35], v[200:201], off
	v_lshl_add_u64 v[200:201], v[200:201], 0, s[100:101]
	global_load_dwordx4 v[36:39], v[200:201], off
	v_lshl_add_u64 v[200:201], v[200:201], 0, s[100:101]
	global_load_dwordx4 v[40:43], v[200:201], off
	v_lshl_add_u64 v[200:201], v[200:201], 0, s[100:101]
	global_load_dwordx4 v[44:47], v[200:201], off
	v_lshl_add_u64 v[200:201], v[200:201], 0, s[100:101]
	global_load_dwordx4 v[48:51], v[200:201], off
	v_lshl_add_u64 v[200:201], v[200:201], 0, s[100:101]
	global_load_dwordx4 v[52:55], v[200:201], off
	v_lshl_add_u64 v[200:201], v[200:201], 0, s[100:101]
	global_load_dwordx4 v[56:59], v[200:201], off
	v_lshl_add_u64 v[200:201], v[200:201], 0, s[100:101]
	global_load_dwordx4 v[60:63], v[200:201], off
	ds_read_b128 v[128:131], v204 offset:0
	ds_read_b128 v[132:135], v204 offset:4352
	ds_read_b128 v[136:139], v204 offset:8704
	ds_read_b128 v[140:143], v204 offset:13056
	s_waitcnt lgkmcnt(3)
	v_lshlrev_b32_e32 v208, 16, v128
	v_and_b32_e32 v209, 0xffff0000, v128
	v_lshlrev_b32_e32 v210, 16, v129
	v_and_b32_e32 v211, 0xffff0000, v129
	v_lshlrev_b32_e32 v212, 16, v130
	v_and_b32_e32 v213, 0xffff0000, v130
	v_lshlrev_b32_e32 v214, 16, v131
	v_and_b32_e32 v215, 0xffff0000, v131
	ds_read_b128 v[128:131], v204 offset:17408
	s_waitcnt vmcnt(15)
	v_lshlrev_b32_e32 v64, 16, v0
	v_and_b32_e32 v65, 0xffff0000, v0
	v_lshlrev_b32_e32 v66, 16, v1
	v_and_b32_e32 v67, 0xffff0000, v1
	v_lshlrev_b32_e32 v68, 16, v2
	v_and_b32_e32 v69, 0xffff0000, v2
	v_lshlrev_b32_e32 v70, 16, v3
	v_and_b32_e32 v71, 0xffff0000, v3
	v_pk_add_f32 v[64:65], v[208:209], v[64:65]
	v_pk_add_f32 v[66:67], v[210:211], v[66:67]
	v_pk_add_f32 v[68:69], v[212:213], v[68:69]
	v_pk_add_f32 v[70:71], v[214:215], v[70:71]
	v_cvt_pk_bf16_f32 v0, v64, v65
	v_cvt_pk_bf16_f32 v1, v66, v67
	v_cvt_pk_bf16_f32 v2, v68, v69
	v_cvt_pk_bf16_f32 v3, v70, v71
	global_store_dwordx4 v[202:203], v[0:3], off
	v_lshl_add_u64 v[202:203], v[202:203], 0, s[100:101]
	s_waitcnt lgkmcnt(3)
	v_lshlrev_b32_e32 v208, 16, v132
	v_and_b32_e32 v209, 0xffff0000, v132
	v_lshlrev_b32_e32 v210, 16, v133
	v_and_b32_e32 v211, 0xffff0000, v133
	v_lshlrev_b32_e32 v212, 16, v134
	v_and_b32_e32 v213, 0xffff0000, v134
	v_lshlrev_b32_e32 v214, 16, v135
	v_and_b32_e32 v215, 0xffff0000, v135
	ds_read_b128 v[132:135], v204 offset:21760
	s_waitcnt vmcnt(14)
	v_lshlrev_b32_e32 v64, 16, v4
	v_and_b32_e32 v65, 0xffff0000, v4
	v_lshlrev_b32_e32 v66, 16, v5
	v_and_b32_e32 v67, 0xffff0000, v5
	v_lshlrev_b32_e32 v68, 16, v6
	v_and_b32_e32 v69, 0xffff0000, v6
	v_lshlrev_b32_e32 v70, 16, v7
	v_and_b32_e32 v71, 0xffff0000, v7
	v_pk_add_f32 v[64:65], v[208:209], v[64:65]
	v_pk_add_f32 v[66:67], v[210:211], v[66:67]
	v_pk_add_f32 v[68:69], v[212:213], v[68:69]
	v_pk_add_f32 v[70:71], v[214:215], v[70:71]
	v_cvt_pk_bf16_f32 v4, v64, v65
	v_cvt_pk_bf16_f32 v5, v66, v67
	v_cvt_pk_bf16_f32 v6, v68, v69
	v_cvt_pk_bf16_f32 v7, v70, v71
	global_store_dwordx4 v[202:203], v[4:7], off
	v_lshl_add_u64 v[202:203], v[202:203], 0, s[100:101]
	s_waitcnt lgkmcnt(3)
	v_lshlrev_b32_e32 v208, 16, v136
	v_and_b32_e32 v209, 0xffff0000, v136
	v_lshlrev_b32_e32 v210, 16, v137
	v_and_b32_e32 v211, 0xffff0000, v137
	v_lshlrev_b32_e32 v212, 16, v138
	v_and_b32_e32 v213, 0xffff0000, v138
	v_lshlrev_b32_e32 v214, 16, v139
	v_and_b32_e32 v215, 0xffff0000, v139
	ds_read_b128 v[136:139], v204 offset:26112
	s_waitcnt vmcnt(13)
	v_lshlrev_b32_e32 v64, 16, v8
	v_and_b32_e32 v65, 0xffff0000, v8
	v_lshlrev_b32_e32 v66, 16, v9
	v_and_b32_e32 v67, 0xffff0000, v9
	v_lshlrev_b32_e32 v68, 16, v10
	v_and_b32_e32 v69, 0xffff0000, v10
	v_lshlrev_b32_e32 v70, 16, v11
	v_and_b32_e32 v71, 0xffff0000, v11
	v_pk_add_f32 v[64:65], v[208:209], v[64:65]
	v_pk_add_f32 v[66:67], v[210:211], v[66:67]
	v_pk_add_f32 v[68:69], v[212:213], v[68:69]
	v_pk_add_f32 v[70:71], v[214:215], v[70:71]
	v_cvt_pk_bf16_f32 v8, v64, v65
	v_cvt_pk_bf16_f32 v9, v66, v67
	v_cvt_pk_bf16_f32 v10, v68, v69
	v_cvt_pk_bf16_f32 v11, v70, v71
	global_store_dwordx4 v[202:203], v[8:11], off
	v_lshl_add_u64 v[202:203], v[202:203], 0, s[100:101]
	s_waitcnt lgkmcnt(3)
	v_lshlrev_b32_e32 v208, 16, v140
	v_and_b32_e32 v209, 0xffff0000, v140
	v_lshlrev_b32_e32 v210, 16, v141
	v_and_b32_e32 v211, 0xffff0000, v141
	v_lshlrev_b32_e32 v212, 16, v142
	v_and_b32_e32 v213, 0xffff0000, v142
	v_lshlrev_b32_e32 v214, 16, v143
	v_and_b32_e32 v215, 0xffff0000, v143
	ds_read_b128 v[140:143], v204 offset:30464
	s_waitcnt vmcnt(12)
; DI int tidx() { int t = __builtin_amdgcn_workitem_id_x(); asm volatile("" : "+v"(t)); return t; }
; DI unsigned cvtpk(float lo, float hi) { const f32x2_ v = {lo, hi}; return __builtin_bit_cast(unsigned, __builtin_convertvector(v, bf16x2_)); }
; DI float bflo(unsigned w) { return __uint_as_float(w << 16); }
; DI float bfhi(unsigned w) { return __uint_as_float(w & 0xffff0000u); }
; DI void phase9(const Params& p, const Sched& sched, unsigned char* smem) {
;     ...
;       const int tid = tidx();
; #pragma unroll
;       for (int i = 0; i < 16; ++i) {
;         const int c = tid + 256 * i, row = c >> 4, ch = (c & 15) * 8;
;         const size_t gi = (size_t)(tm * 256 + row) * 1024 + tn * 128 + ch;
;         const u32x4 sv = *(const u32x4*)(Ls + row * EST + ch), xv = *(const u32x4*)(x1b + gi);
;         u32x4 w;
;         w.x = cvtpk(bflo(xv.x) + bflo(sv.x), bfhi(xv.x) + bfhi(sv.x)); w.y = cvtpk(bflo(xv.y) + bflo(sv.y), bfhi(xv.y) + bfhi(sv.y));
;         w.z = cvtpk(bflo(xv.z) + bflo(sv.z), bfhi(xv.z) + bfhi(sv.z)); w.w = cvtpk(bflo(xv.w) + bflo(sv.w), bfhi(xv.w) + bfhi(sv.w));
;         *(u32x4*)(x2b + gi) = w;
;       }
	v_lshlrev_b32_e32 v64, 16, v12
	v_and_b32_e32 v65, 0xffff0000, v12
	v_lshlrev_b32_e32 v66, 16, v13
	v_and_b32_e32 v67, 0xffff0000, v13
	v_lshlrev_b32_e32 v68, 16, v14
	v_and_b32_e32 v69, 0xffff0000, v14
	v_lshlrev_b32_e32 v70, 16, v15
	v_and_b32_e32 v71, 0xffff0000, v15
	v_pk_add_f32 v[64:65], v[208:209], v[64:65]
	v_pk_add_f32 v[66:67], v[210:211], v[66:67]
	v_pk_add_f32 v[68:69], v[212:213], v[68:69]
	v_pk_add_f32 v[70:71], v[214:215], v[70:71]
	v_cvt_pk_bf16_f32 v12, v64, v65
	v_cvt_pk_bf16_f32 v13, v66, v67
	v_cvt_pk_bf16_f32 v14, v68, v69
	v_cvt_pk_bf16_f32 v15, v70, v71
	global_store_dwordx4 v[202:203], v[12:15], off
	v_lshl_add_u64 v[202:203], v[202:203], 0, s[100:101]
	s_waitcnt lgkmcnt(3)
	v_lshlrev_b32_e32 v208, 16, v128
	v_and_b32_e32 v209, 0xffff0000, v128
	v_lshlrev_b32_e32 v210, 16, v129
	v_and_b32_e32 v211, 0xffff0000, v129
	v_lshlrev_b32_e32 v212, 16, v130
	v_and_b32_e32 v213, 0xffff0000, v130
	v_lshlrev_b32_e32 v214, 16, v131
	v_and_b32_e32 v215, 0xffff0000, v131
	ds_read_b128 v[128:131], v204 offset:34816
	s_waitcnt vmcnt(11)
	v_lshlrev_b32_e32 v64, 16, v16
	v_and_b32_e32 v65, 0xffff0000, v16
	v_lshlrev_b32_e32 v66, 16, v17
	v_and_b32_e32 v67, 0xffff0000, v17
	v_lshlrev_b32_e32 v68, 16, v18
	v_and_b32_e32 v69, 0xffff0000, v18
	v_lshlrev_b32_e32 v70, 16, v19
	v_and_b32_e32 v71, 0xffff0000, v19
	v_pk_add_f32 v[64:65], v[208:209], v[64:65]
	v_pk_add_f32 v[66:67], v[210:211], v[66:67]
	v_pk_add_f32 v[68:69], v[212:213], v[68:69]
	v_pk_add_f32 v[70:71], v[214:215], v[70:71]
	v_cvt_pk_bf16_f32 v16, v64, v65
	v_cvt_pk_bf16_f32 v17, v66, v67
	v_cvt_pk_bf16_f32 v18, v68, v69
	v_cvt_pk_bf16_f32 v19, v70, v71
	global_store_dwordx4 v[202:203], v[16:19], off
	v_lshl_add_u64 v[202:203], v[202:203], 0, s[100:101]
	s_waitcnt lgkmcnt(3)
	v_lshlrev_b32_e32 v208, 16, v132
	v_and_b32_e32 v209, 0xffff0000, v132
	v_lshlrev_b32_e32 v210, 16, v133
	v_and_b32_e32 v211, 0xffff0000, v133
	v_lshlrev_b32_e32 v212, 16, v134
	v_and_b32_e32 v213, 0xffff0000, v134
	v_lshlrev_b32_e32 v214, 16, v135
	v_and_b32_e32 v215, 0xffff0000, v135
	ds_read_b128 v[132:135], v204 offset:39168
	s_waitcnt vmcnt(10)
	v_lshlrev_b32_e32 v64, 16, v20
	v_and_b32_e32 v65, 0xffff0000, v20
	v_lshlrev_b32_e32 v66, 16, v21
	v_and_b32_e32 v67, 0xffff0000, v21
	v_lshlrev_b32_e32 v68, 16, v22
	v_and_b32_e32 v69, 0xffff0000, v22
	v_lshlrev_b32_e32 v70, 16, v23
	v_and_b32_e32 v71, 0xffff0000, v23
	v_pk_add_f32 v[64:65], v[208:209], v[64:65]
	v_pk_add_f32 v[66:67], v[210:211], v[66:67]
	v_pk_add_f32 v[68:69], v[212:213], v[68:69]
	v_pk_add_f32 v[70:71], v[214:215], v[70:71]
	v_cvt_pk_bf16_f32 v20, v64, v65
	v_cvt_pk_bf16_f32 v21, v66, v67
	v_cvt_pk_bf16_f32 v22, v68, v69
	v_cvt_pk_bf16_f32 v23, v70, v71
	global_store_dwordx4 v[202:203], v[20:23], off
	v_lshl_add_u64 v[202:203], v[202:203], 0, s[100:101]
	s_waitcnt lgkmcnt(3)
	v_lshlrev_b32_e32 v208, 16, v136
	v_and_b32_e32 v209, 0xffff0000, v136
	v_lshlrev_b32_e32 v210, 16, v137
	v_and_b32_e32 v211, 0xffff0000, v137
	v_lshlrev_b32_e32 v212, 16, v138
	v_and_b32_e32 v213, 0xffff0000, v138
	v_lshlrev_b32_e32 v214, 16, v139
	v_and_b32_e32 v215, 0xffff0000, v139
	ds_read_b128 v[136:139], v204 offset:43520
	s_waitcnt vmcnt(9)
	v_lshlrev_b32_e32 v64, 16, v24
	v_and_b32_e32 v65, 0xffff0000, v24
	v_lshlrev_b32_e32 v66, 16, v25
	v_and_b32_e32 v67, 0xffff0000, v25
	v_lshlrev_b32_e32 v68, 16, v26
	v_and_b32_e32 v69, 0xffff0000, v26
	v_lshlrev_b32_e32 v70, 16, v27
	v_and_b32_e32 v71, 0xffff0000, v27
	v_pk_add_f32 v[64:65], v[208:209], v[64:65]
	v_pk_add_f32 v[66:67], v[210:211], v[66:67]
	v_pk_add_f32 v[68:69], v[212:213], v[68:69]
	v_pk_add_f32 v[70:71], v[214:215], v[70:71]
	v_cvt_pk_bf16_f32 v24, v64, v65
	v_cvt_pk_bf16_f32 v25, v66, v67
	v_cvt_pk_bf16_f32 v26, v68, v69
	v_cvt_pk_bf16_f32 v27, v70, v71
	global_store_dwordx4 v[202:203], v[24:27], off
	v_lshl_add_u64 v[202:203], v[202:203], 0, s[100:101]
	s_waitcnt lgkmcnt(3)
	v_lshlrev_b32_e32 v208, 16, v140
	v_and_b32_e32 v209, 0xffff0000, v140
	v_lshlrev_b32_e32 v210, 16, v141
	v_and_b32_e32 v211, 0xffff0000, v141
	v_lshlrev_b32_e32 v212, 16, v142
	v_and_b32_e32 v213, 0xffff0000, v142
	v_lshlrev_b32_e32 v214, 16, v143
	v_and_b32_e32 v215, 0xffff0000, v143
	ds_read_b128 v[140:143], v204 offset:47872
	s_waitcnt vmcnt(8)
	v_lshlrev_b32_e32 v64, 16, v28
	v_and_b32_e32 v65, 0xffff0000, v28
	v_lshlrev_b32_e32 v66, 16, v29
	v_and_b32_e32 v67, 0xffff0000, v29
	v_lshlrev_b32_e32 v68, 16, v30
	v_and_b32_e32 v69, 0xffff0000, v30
	v_lshlrev_b32_e32 v70, 16, v31
	v_and_b32_e32 v71, 0xffff0000, v31
	v_pk_add_f32 v[64:65], v[208:209], v[64:65]
	v_pk_add_f32 v[66:67], v[210:211], v[66:67]
	v_pk_add_f32 v[68:69], v[212:213], v[68:69]
	v_pk_add_f32 v[70:71], v[214:215], v[70:71]
	v_cvt_pk_bf16_f32 v28, v64, v65
	v_cvt_pk_bf16_f32 v29, v66, v67
	v_cvt_pk_bf16_f32 v30, v68, v69
	v_cvt_pk_bf16_f32 v31, v70, v71
	global_store_dwordx4 v[202:203], v[28:31], off
	v_lshl_add_u64 v[202:203], v[202:203], 0, s[100:101]
	s_waitcnt lgkmcnt(3)
	v_lshlrev_b32_e32 v208, 16, v128
	v_and_b32_e32 v209, 0xffff0000, v128
	v_lshlrev_b32_e32 v210, 16, v129
	v_and_b32_e32 v211, 0xffff0000, v129
	v_lshlrev_b32_e32 v212, 16, v130
	v_and_b32_e32 v213, 0xffff0000, v130
	v_lshlrev_b32_e32 v214, 16, v131
	v_and_b32_e32 v215, 0xffff0000, v131
	ds_read_b128 v[128:131], v204 offset:52224
	s_waitcnt vmcnt(7)
; DI int tidx() { int t = __builtin_amdgcn_workitem_id_x(); asm volatile("" : "+v"(t)); return t; }
; DI unsigned cvtpk(float lo, float hi) { const f32x2_ v = {lo, hi}; return __builtin_bit_cast(unsigned, __builtin_convertvector(v, bf16x2_)); }
; DI float bflo(unsigned w) { return __uint_as_float(w << 16); }
; DI float bfhi(unsigned w) { return __uint_as_float(w & 0xffff0000u); }
; DI void phase9(const Params& p, const Sched& sched, unsigned char* smem) {
;     ...
;       const int tid = tidx();
; #pragma unroll
;       for (int i = 0; i < 16; ++i) {
;         const int c = tid + 256 * i, row = c >> 4, ch = (c & 15) * 8;
;         const size_t gi = (size_t)(tm * 256 + row) * 1024 + tn * 128 + ch;
;         const u32x4 sv = *(const u32x4*)(Ls + row * EST + ch), xv = *(const u32x4*)(x1b + gi);
;         u32x4 w;
;         w.x = cvtpk(bflo(xv.x) + bflo(sv.x), bfhi(xv.x) + bfhi(sv.x)); w.y = cvtpk(bflo(xv.y) + bflo(sv.y), bfhi(xv.y) + bfhi(sv.y));
;         w.z = cvtpk(bflo(xv.z) + bflo(sv.z), bfhi(xv.z) + bfhi(sv.z)); w.w = cvtpk(bflo(xv.w) + bflo(sv.w), bfhi(xv.w) + bfhi(sv.w));
;         *(u32x4*)(x2b + gi) = w;
;       }
	v_lshlrev_b32_e32 v64, 16, v32
	v_and_b32_e32 v65, 0xffff0000, v32
	v_lshlrev_b32_e32 v66, 16, v33
	v_and_b32_e32 v67, 0xffff0000, v33
	v_lshlrev_b32_e32 v68, 16, v34
	v_and_b32_e32 v69, 0xffff0000, v34
	v_lshlrev_b32_e32 v70, 16, v35
	v_and_b32_e32 v71, 0xffff0000, v35
	v_pk_add_f32 v[64:65], v[208:209], v[64:65]
	v_pk_add_f32 v[66:67], v[210:211], v[66:67]
	v_pk_add_f32 v[68:69], v[212:213], v[68:69]
	v_pk_add_f32 v[70:71], v[214:215], v[70:71]
	v_cvt_pk_bf16_f32 v32, v64, v65
	v_cvt_pk_bf16_f32 v33, v66, v67
	v_cvt_pk_bf16_f32 v34, v68, v69
	v_cvt_pk_bf16_f32 v35, v70, v71
	global_store_dwordx4 v[202:203], v[32:35], off
	v_lshl_add_u64 v[202:203], v[202:203], 0, s[100:101]
	s_waitcnt lgkmcnt(3)
	v_lshlrev_b32_e32 v208, 16, v132
	v_and_b32_e32 v209, 0xffff0000, v132
	v_lshlrev_b32_e32 v210, 16, v133
	v_and_b32_e32 v211, 0xffff0000, v133
	v_lshlrev_b32_e32 v212, 16, v134
	v_and_b32_e32 v213, 0xffff0000, v134
	v_lshlrev_b32_e32 v214, 16, v135
	v_and_b32_e32 v215, 0xffff0000, v135
	ds_read_b128 v[132:135], v204 offset:56576
	s_waitcnt vmcnt(6)
	v_lshlrev_b32_e32 v64, 16, v36
	v_and_b32_e32 v65, 0xffff0000, v36
	v_lshlrev_b32_e32 v66, 16, v37
	v_and_b32_e32 v67, 0xffff0000, v37
	v_lshlrev_b32_e32 v68, 16, v38
	v_and_b32_e32 v69, 0xffff0000, v38
	v_lshlrev_b32_e32 v70, 16, v39
	v_and_b32_e32 v71, 0xffff0000, v39
	v_pk_add_f32 v[64:65], v[208:209], v[64:65]
	v_pk_add_f32 v[66:67], v[210:211], v[66:67]
	v_pk_add_f32 v[68:69], v[212:213], v[68:69]
	v_pk_add_f32 v[70:71], v[214:215], v[70:71]
	v_cvt_pk_bf16_f32 v36, v64, v65
	v_cvt_pk_bf16_f32 v37, v66, v67
	v_cvt_pk_bf16_f32 v38, v68, v69
	v_cvt_pk_bf16_f32 v39, v70, v71
	global_store_dwordx4 v[202:203], v[36:39], off
	v_lshl_add_u64 v[202:203], v[202:203], 0, s[100:101]
	s_waitcnt lgkmcnt(3)
	v_lshlrev_b32_e32 v208, 16, v136
	v_and_b32_e32 v209, 0xffff0000, v136
	v_lshlrev_b32_e32 v210, 16, v137
	v_and_b32_e32 v211, 0xffff0000, v137
	v_lshlrev_b32_e32 v212, 16, v138
	v_and_b32_e32 v213, 0xffff0000, v138
	v_lshlrev_b32_e32 v214, 16, v139
	v_and_b32_e32 v215, 0xffff0000, v139
	ds_read_b128 v[136:139], v204 offset:60928
	s_waitcnt vmcnt(5)
	v_lshlrev_b32_e32 v64, 16, v40
	v_and_b32_e32 v65, 0xffff0000, v40
	v_lshlrev_b32_e32 v66, 16, v41
	v_and_b32_e32 v67, 0xffff0000, v41
	v_lshlrev_b32_e32 v68, 16, v42
	v_and_b32_e32 v69, 0xffff0000, v42
	v_lshlrev_b32_e32 v70, 16, v43
	v_and_b32_e32 v71, 0xffff0000, v43
	v_pk_add_f32 v[64:65], v[208:209], v[64:65]
	v_pk_add_f32 v[66:67], v[210:211], v[66:67]
	v_pk_add_f32 v[68:69], v[212:213], v[68:69]
	v_pk_add_f32 v[70:71], v[214:215], v[70:71]
	v_cvt_pk_bf16_f32 v40, v64, v65
	v_cvt_pk_bf16_f32 v41, v66, v67
	v_cvt_pk_bf16_f32 v42, v68, v69
	v_cvt_pk_bf16_f32 v43, v70, v71
	global_store_dwordx4 v[202:203], v[40:43], off
	v_lshl_add_u64 v[202:203], v[202:203], 0, s[100:101]
	s_waitcnt lgkmcnt(3)
	v_lshlrev_b32_e32 v208, 16, v140
	v_and_b32_e32 v209, 0xffff0000, v140
	v_lshlrev_b32_e32 v210, 16, v141
	v_and_b32_e32 v211, 0xffff0000, v141
	v_lshlrev_b32_e32 v212, 16, v142
	v_and_b32_e32 v213, 0xffff0000, v142
	v_lshlrev_b32_e32 v214, 16, v143
	v_and_b32_e32 v215, 0xffff0000, v143
	ds_read_b128 v[140:143], v204 offset:65280
	s_waitcnt vmcnt(4)
	v_lshlrev_b32_e32 v64, 16, v44
	v_and_b32_e32 v65, 0xffff0000, v44
	v_lshlrev_b32_e32 v66, 16, v45
	v_and_b32_e32 v67, 0xffff0000, v45
	v_lshlrev_b32_e32 v68, 16, v46
	v_and_b32_e32 v69, 0xffff0000, v46
	v_lshlrev_b32_e32 v70, 16, v47
	v_and_b32_e32 v71, 0xffff0000, v47
	v_pk_add_f32 v[64:65], v[208:209], v[64:65]
	v_pk_add_f32 v[66:67], v[210:211], v[66:67]
	v_pk_add_f32 v[68:69], v[212:213], v[68:69]
	v_pk_add_f32 v[70:71], v[214:215], v[70:71]
	v_cvt_pk_bf16_f32 v44, v64, v65
	v_cvt_pk_bf16_f32 v45, v66, v67
	v_cvt_pk_bf16_f32 v46, v68, v69
	v_cvt_pk_bf16_f32 v47, v70, v71
	global_store_dwordx4 v[202:203], v[44:47], off
	v_lshl_add_u64 v[202:203], v[202:203], 0, s[100:101]
	s_waitcnt lgkmcnt(3)
; DI int tidx() { int t = __builtin_amdgcn_workitem_id_x(); asm volatile("" : "+v"(t)); return t; }
; DI unsigned cvtpk(float lo, float hi) { const f32x2_ v = {lo, hi}; return __builtin_bit_cast(unsigned, __builtin_convertvector(v, bf16x2_)); }
; DI float bflo(unsigned w) { return __uint_as_float(w << 16); }
; DI float bfhi(unsigned w) { return __uint_as_float(w & 0xffff0000u); }
; DI void phase9(const Params& p, const Sched& sched, unsigned char* smem) {
;     ...
;       const int tid = tidx();
; #pragma unroll
;       for (int i = 0; i < 16; ++i) {
;         const int c = tid + 256 * i, row = c >> 4, ch = (c & 15) * 8;
;         const size_t gi = (size_t)(tm * 256 + row) * 1024 + tn * 128 + ch;
;         const u32x4 sv = *(const u32x4*)(Ls + row * EST + ch), xv = *(const u32x4*)(x1b + gi);
;         u32x4 w;
;         w.x = cvtpk(bflo(xv.x) + bflo(sv.x), bfhi(xv.x) + bfhi(sv.x)); w.y = cvtpk(bflo(xv.y) + bflo(sv.y), bfhi(xv.y) + bfhi(sv.y));
;         w.z = cvtpk(bflo(xv.z) + bflo(sv.z), bfhi(xv.z) + bfhi(sv.z)); w.w = cvtpk(bflo(xv.w) + bflo(sv.w), bfhi(xv.w) + bfhi(sv.w));
;         *(u32x4*)(x2b + gi) = w;
;       }
	v_lshlrev_b32_e32 v208, 16, v128
	v_and_b32_e32 v209, 0xffff0000, v128
	v_lshlrev_b32_e32 v210, 16, v129
	v_and_b32_e32 v211, 0xffff0000, v129
	v_lshlrev_b32_e32 v212, 16, v130
	v_and_b32_e32 v213, 0xffff0000, v130
	v_lshlrev_b32_e32 v214, 16, v131
	v_and_b32_e32 v215, 0xffff0000, v131
	s_waitcnt vmcnt(3)
	v_lshlrev_b32_e32 v64, 16, v48
	v_and_b32_e32 v65, 0xffff0000, v48
	v_lshlrev_b32_e32 v66, 16, v49
	v_and_b32_e32 v67, 0xffff0000, v49
	v_lshlrev_b32_e32 v68, 16, v50
	v_and_b32_e32 v69, 0xffff0000, v50
	v_lshlrev_b32_e32 v70, 16, v51
	v_and_b32_e32 v71, 0xffff0000, v51
	v_pk_add_f32 v[64:65], v[208:209], v[64:65]
	v_pk_add_f32 v[66:67], v[210:211], v[66:67]
	v_pk_add_f32 v[68:69], v[212:213], v[68:69]
	v_pk_add_f32 v[70:71], v[214:215], v[70:71]
	v_cvt_pk_bf16_f32 v48, v64, v65
	v_cvt_pk_bf16_f32 v49, v66, v67
	v_cvt_pk_bf16_f32 v50, v68, v69
	v_cvt_pk_bf16_f32 v51, v70, v71
	global_store_dwordx4 v[202:203], v[48:51], off
	v_lshl_add_u64 v[202:203], v[202:203], 0, s[100:101]
	s_waitcnt lgkmcnt(2)
	v_lshlrev_b32_e32 v208, 16, v132
	v_and_b32_e32 v209, 0xffff0000, v132
	v_lshlrev_b32_e32 v210, 16, v133
	v_and_b32_e32 v211, 0xffff0000, v133
	v_lshlrev_b32_e32 v212, 16, v134
	v_and_b32_e32 v213, 0xffff0000, v134
	v_lshlrev_b32_e32 v214, 16, v135
	v_and_b32_e32 v215, 0xffff0000, v135
	s_waitcnt vmcnt(2)
	v_lshlrev_b32_e32 v64, 16, v52
	v_and_b32_e32 v65, 0xffff0000, v52
	v_lshlrev_b32_e32 v66, 16, v53
	v_and_b32_e32 v67, 0xffff0000, v53
	v_lshlrev_b32_e32 v68, 16, v54
	v_and_b32_e32 v69, 0xffff0000, v54
	v_lshlrev_b32_e32 v70, 16, v55
	v_and_b32_e32 v71, 0xffff0000, v55
	v_pk_add_f32 v[64:65], v[208:209], v[64:65]
	v_pk_add_f32 v[66:67], v[210:211], v[66:67]
	v_pk_add_f32 v[68:69], v[212:213], v[68:69]
	v_pk_add_f32 v[70:71], v[214:215], v[70:71]
	v_cvt_pk_bf16_f32 v52, v64, v65
	v_cvt_pk_bf16_f32 v53, v66, v67
	v_cvt_pk_bf16_f32 v54, v68, v69
	v_cvt_pk_bf16_f32 v55, v70, v71
	global_store_dwordx4 v[202:203], v[52:55], off
	v_lshl_add_u64 v[202:203], v[202:203], 0, s[100:101]
	s_waitcnt lgkmcnt(1)
	v_lshlrev_b32_e32 v208, 16, v136
	v_and_b32_e32 v209, 0xffff0000, v136
	v_lshlrev_b32_e32 v210, 16, v137
	v_and_b32_e32 v211, 0xffff0000, v137
	v_lshlrev_b32_e32 v212, 16, v138
	v_and_b32_e32 v213, 0xffff0000, v138
	v_lshlrev_b32_e32 v214, 16, v139
	v_and_b32_e32 v215, 0xffff0000, v139
	s_waitcnt vmcnt(1)
	v_lshlrev_b32_e32 v64, 16, v56
	v_and_b32_e32 v65, 0xffff0000, v56
	v_lshlrev_b32_e32 v66, 16, v57
	v_and_b32_e32 v67, 0xffff0000, v57
	v_lshlrev_b32_e32 v68, 16, v58
	v_and_b32_e32 v69, 0xffff0000, v58
	v_lshlrev_b32_e32 v70, 16, v59
	v_and_b32_e32 v71, 0xffff0000, v59
	v_pk_add_f32 v[64:65], v[208:209], v[64:65]
	v_pk_add_f32 v[66:67], v[210:211], v[66:67]
	v_pk_add_f32 v[68:69], v[212:213], v[68:69]
	v_pk_add_f32 v[70:71], v[214:215], v[70:71]
	v_cvt_pk_bf16_f32 v56, v64, v65
	v_cvt_pk_bf16_f32 v57, v66, v67
	v_cvt_pk_bf16_f32 v58, v68, v69
	v_cvt_pk_bf16_f32 v59, v70, v71
	global_store_dwordx4 v[202:203], v[56:59], off
	v_lshl_add_u64 v[202:203], v[202:203], 0, s[100:101]
	s_waitcnt lgkmcnt(0)
	v_lshlrev_b32_e32 v208, 16, v140
	v_and_b32_e32 v209, 0xffff0000, v140
	v_lshlrev_b32_e32 v210, 16, v141
	v_and_b32_e32 v211, 0xffff0000, v141
	v_lshlrev_b32_e32 v212, 16, v142
	v_and_b32_e32 v213, 0xffff0000, v142
	v_lshlrev_b32_e32 v214, 16, v143
	v_and_b32_e32 v215, 0xffff0000, v143
	s_waitcnt vmcnt(0)
	v_lshlrev_b32_e32 v64, 16, v60
	v_and_b32_e32 v65, 0xffff0000, v60
	v_lshlrev_b32_e32 v66, 16, v61
	v_and_b32_e32 v67, 0xffff0000, v61
	v_lshlrev_b32_e32 v68, 16, v62
	v_and_b32_e32 v69, 0xffff0000, v62
	v_lshlrev_b32_e32 v70, 16, v63
	v_and_b32_e32 v71, 0xffff0000, v63
	v_pk_add_f32 v[64:65], v[208:209], v[64:65]
	v_pk_add_f32 v[66:67], v[210:211], v[66:67]
	v_pk_add_f32 v[68:69], v[212:213], v[68:69]
	v_pk_add_f32 v[70:71], v[214:215], v[70:71]
	v_cvt_pk_bf16_f32 v60, v64, v65
	v_cvt_pk_bf16_f32 v61, v66, v67
	v_cvt_pk_bf16_f32 v62, v68, v69
	v_cvt_pk_bf16_f32 v63, v70, v71
	global_store_dwordx4 v[202:203], v[60:63], off
	s_cbranch_scc0 .LBB0_1094
	s_branch .LBB0_1091
